# sample-gemm tails: row-stat / residual loads issued at unit start (oldest in vmcnt order) instead of after the split-K reduce barrier, all 8 sample gemms
# baseline (speedup 1.0000x reference)
; DI float row_rstd(const float* SS, int row) { return rsqrtf(SS[row] * (1.0f / 1024.0f) + 1e-6f); }
;     DI void operator()(const f32x4 vraw, int row, int pn, int wc, int bj, int cl) const {
;         const f32x4 v = vraw * row_rstd(SS, row);
; template <class EpiS>
; DI void sample_gemm(LAS unsigned char* lds, const bf16_t* A, const bf16_t* Bt, int nN, int K, const EpiS& E) {
;     ...
;     for (int un = (int)blockIdx.x; un < nunits; un += (int)gridDim.x) {
;         const int rb = un & 3, wc = (un >> 2) & 3, pn = un >> 4;
;         const bf16_t* ap = A + (size_t)(MP + rb * 32 + r32) * K + w * kw + h * 8;
;         const bf16_t* b0p = Bt + (size_t)(pn * 256 + wc * 32 + r32) * K + w * kw + h * 8;
;         const bf16_t* b1p = b0p + (size_t)128 * K;
;         f32x16 c0, c1;
; #pragma unroll
;         for (int r = 0; r < 16; ++r) { c0[r] = 0.f; c1[r] = 0.f; }
; #pragma unroll 8
;         for (int ks = 0; ks < nk; ++ks) {
;             const bf16x8 a = *(const bf16x8*)(ap + ks * 16), b0 = *(const bf16x8*)(b0p + ks * 16), b1 = *(const bf16x8*)(b1p + ks * 16);
;             c0 = __builtin_amdgcn_mfma_f32_32x32x16_bf16(a, b0, c0, 0, 0, 0);
;             c1 = __builtin_amdgcn_mfma_f32_32x32x16_bf16(a, b1, c1, 0, 0, 0);
;         }
.LBB0_339:
	s_and_b32 s4, s33, 0x60
	s_or_b32 s50, s4, 0x8000
	v_or_b32_e32 v3, s50, v42
	s_ashr_i32 s71, s69, 4
	s_and_b32 s70, s8, 0x60
	v_lshlrev_b32_e32 v34, 11, v3
	s_lshl_b32 s4, s71, 8
	v_or_b32_e32 v2, s70, v42
	v_lshl_add_u64 v[76:77], v[36:37], 0, v[34:35]
	v_or_b32_e32 v2, s4, v2
	v_ashrrev_i32_e32 v3, 31, v2
	v_lshlrev_b64 v[2:3], 11, v[2:3]
	v_lshl_add_u64 v[78:79], v[38:39], 0, v[2:3]
	v_add_co_u32_e32 v80, vcc, s67, v78
	v_add_u32_e32 v41, s50, v1
	s_nop 0
	v_addc_co_u32_e32 v81, vcc, 0, v79, vcc
	v_lshlrev_b32_e32 v34, 2, v41
	s_cmp_gt_i32 s71, 7
	s_waitcnt vmcnt(6) lgkmcnt(0)
	global_load_dword v34, v34, s[6:7]
	v_lshl_add_u64 v[158:159], v[76:77], 0, v[182:183]
	v_lshl_add_u64 v[160:161], v[78:79], 0, v[182:183]
	v_lshl_add_u64 v[180:181], v[80:81], 0, v[182:183]
	global_load_dwordx4 v[82:85], v[158:159], off
	v_lshl_add_u64 v[158:159], v[158:159], 0, s[80:81]
	global_load_dwordx4 v[86:89], v[158:159], off
	v_lshl_add_u64 v[158:159], v[158:159], 0, s[80:81]
	global_load_dwordx4 v[90:93], v[158:159], off
	v_lshl_add_u64 v[158:159], v[158:159], 0, s[80:81]
	global_load_dwordx4 v[94:97], v[158:159], off
	v_lshl_add_u64 v[158:159], v[158:159], 0, s[82:83]
	global_load_dwordx4 v[98:101], v[160:161], off
	v_lshl_add_u64 v[160:161], v[160:161], 0, s[80:81]
	global_load_dwordx4 v[102:105], v[160:161], off
	v_lshl_add_u64 v[160:161], v[160:161], 0, s[80:81]
	global_load_dwordx4 v[106:109], v[160:161], off
	v_lshl_add_u64 v[160:161], v[160:161], 0, s[80:81]
	global_load_dwordx4 v[110:113], v[160:161], off
	v_lshl_add_u64 v[160:161], v[160:161], 0, s[82:83]
	global_load_dwordx4 v[132:135], v[180:181], off
	v_lshl_add_u64 v[180:181], v[180:181], 0, s[80:81]
	global_load_dwordx4 v[136:139], v[180:181], off
	v_lshl_add_u64 v[180:181], v[180:181], 0, s[80:81]
	global_load_dwordx4 v[140:143], v[180:181], off
	v_lshl_add_u64 v[180:181], v[180:181], 0, s[80:81]
	global_load_dwordx4 v[144:147], v[180:181], off
	v_lshl_add_u64 v[180:181], v[180:181], 0, s[82:83]
	global_load_dwordx4 v[148:151], v[158:159], off offset:128
	v_lshl_add_u64 v[158:159], v[158:159], 0, s[80:81]
	global_load_dwordx4 v[166:169], v[158:159], off offset:128
	v_lshl_add_u64 v[158:159], v[158:159], 0, s[80:81]
	global_load_dwordx4 v[170:173], v[158:159], off offset:128
	v_lshl_add_u64 v[158:159], v[158:159], 0, s[80:81]
	global_load_dwordx4 v[174:177], v[158:159], off offset:128
	global_load_dwordx4 v[198:201], v[160:161], off offset:128
	v_lshl_add_u64 v[160:161], v[160:161], 0, s[80:81]
	global_load_dwordx4 v[202:205], v[160:161], off offset:128
	v_lshl_add_u64 v[160:161], v[160:161], 0, s[80:81]
	global_load_dwordx4 v[216:219], v[160:161], off offset:128
	v_lshl_add_u64 v[160:161], v[160:161], 0, s[80:81]
	global_load_dwordx4 v[220:223], v[160:161], off offset:128
	global_load_dwordx4 v[224:227], v[180:181], off offset:128
	v_lshl_add_u64 v[180:181], v[180:181], 0, s[80:81]
	global_load_dwordx4 v[228:231], v[180:181], off offset:128
	v_lshl_add_u64 v[180:181], v[180:181], 0, s[80:81]
	global_load_dwordx4 v[232:235], v[180:181], off offset:128
	v_lshl_add_u64 v[180:181], v[180:181], 0, s[80:81]
	global_load_dwordx4 v[236:239], v[180:181], off offset:128
	s_waitcnt vmcnt(16)
	ds_write_b128 v194, v[82:85]
	ds_write_b128 v195, v[86:89] offset:1024
	ds_write_b128 v194, v[90:93] offset:2048
	ds_write_b128 v195, v[94:97] offset:3072
	ds_write_b128 v194, v[98:101] offset:4096
	ds_write_b128 v195, v[102:105] offset:5120
	ds_write_b128 v194, v[106:109] offset:6144
	ds_write_b128 v195, v[110:113] offset:7168
	ds_read_b128 v[82:85], v244
	ds_read_b128 v[86:89], v245
	ds_read_b128 v[90:93], v246
	ds_read_b128 v[94:97], v193
	ds_read_b128 v[98:101], v244 offset:4096
	ds_read_b128 v[102:105], v245 offset:4096
	ds_read_b128 v[106:109], v246 offset:4096
	ds_read_b128 v[110:113], v193 offset:4096
	s_waitcnt lgkmcnt(0)
	v_mfma_f32_32x32x16_bf16 v[2:17], v[82:85], v[98:101], 0
	v_mfma_f32_32x32x16_bf16 v[2:17], v[86:89], v[102:105], v[2:17]
	v_mfma_f32_32x32x16_bf16 v[2:17], v[90:93], v[106:109], v[2:17]
	v_mfma_f32_32x32x16_bf16 v[2:17], v[94:97], v[110:113], v[2:17]
	s_waitcnt vmcnt(12)
	ds_write_b128 v194, v[132:135] offset:4096
	ds_write_b128 v195, v[136:139] offset:5120
	ds_write_b128 v194, v[140:143] offset:6144
	ds_write_b128 v195, v[144:147] offset:7168
	ds_read_b128 v[132:135], v244 offset:4096
	ds_read_b128 v[136:139], v245 offset:4096
	ds_read_b128 v[140:143], v246 offset:4096
	ds_read_b128 v[144:147], v193 offset:4096
	s_waitcnt lgkmcnt(0)
	v_mfma_f32_32x32x16_bf16 v[18:33], v[82:85], v[132:135], 0
	v_mfma_f32_32x32x16_bf16 v[18:33], v[86:89], v[136:139], v[18:33]
	v_mfma_f32_32x32x16_bf16 v[18:33], v[90:93], v[140:143], v[18:33]
	v_mfma_f32_32x32x16_bf16 v[18:33], v[94:97], v[144:147], v[18:33]
	s_waitcnt vmcnt(4)
	ds_write_b128 v194, v[148:151]
	ds_write_b128 v195, v[166:169] offset:1024
	ds_write_b128 v194, v[170:173] offset:2048
	ds_write_b128 v195, v[174:177] offset:3072
	ds_write_b128 v194, v[198:201] offset:4096
	ds_write_b128 v195, v[202:205] offset:5120
	ds_write_b128 v194, v[216:219] offset:6144
	ds_write_b128 v195, v[220:223] offset:7168
	ds_read_b128 v[148:151], v244
	ds_read_b128 v[166:169], v245
	ds_read_b128 v[170:173], v246
	ds_read_b128 v[174:177], v193
	ds_read_b128 v[198:201], v244 offset:4096
	ds_read_b128 v[202:205], v245 offset:4096
	ds_read_b128 v[216:219], v246 offset:4096
	ds_read_b128 v[220:223], v193 offset:4096
	s_waitcnt lgkmcnt(0)
	v_mfma_f32_32x32x16_bf16 v[2:17], v[148:151], v[198:201], v[2:17]
	v_mfma_f32_32x32x16_bf16 v[2:17], v[166:169], v[202:205], v[2:17]
	v_mfma_f32_32x32x16_bf16 v[2:17], v[170:173], v[216:219], v[2:17]
	v_mfma_f32_32x32x16_bf16 v[2:17], v[174:177], v[220:223], v[2:17]
	s_waitcnt vmcnt(0)
	ds_write_b128 v194, v[224:227] offset:4096
	ds_write_b128 v195, v[228:231] offset:5120
	ds_write_b128 v194, v[232:235] offset:6144
	ds_write_b128 v195, v[236:239] offset:7168
	ds_read_b128 v[224:227], v244 offset:4096
	ds_read_b128 v[228:231], v245 offset:4096
	ds_read_b128 v[232:235], v246 offset:4096
	ds_read_b128 v[236:239], v193 offset:4096
	s_waitcnt lgkmcnt(0)
	v_mfma_f32_32x32x16_bf16 v[18:33], v[148:151], v[224:227], v[18:33]
	v_mfma_f32_32x32x16_bf16 v[18:33], v[166:169], v[228:231], v[18:33]
	v_mfma_f32_32x32x16_bf16 v[18:33], v[170:173], v[232:235], v[18:33]
	v_mfma_f32_32x32x16_bf16 v[18:33], v[174:177], v[236:239], v[18:33]
	s_barrier
; #define LAS __attribute__((address_space(3)))
; DI float row_rstd(const float* SS, int row) { return rsqrtf(SS[row] * (1.0f / 1024.0f) + 1e-6f); }
; DI f32x4 shx8(const f32x4 v) { f32x4 o; o[0] = __shfl_xor(v[0], 8); o[1] = __shfl_xor(v[1], 8); o[2] = __shfl_xor(v[2], 8); o[3] = __shfl_xor(v[3], 8); return o; }
;     DI void operator()(const f32x4 vraw, int row, int pn, int wc, int bj, int cl) const {
;         const f32x4 v = vraw * row_rstd(SS, row);
;         const f32x4 o = shx8(v);
; template <class EpiS>
; DI void sample_gemm(LAS unsigned char* lds, const bf16_t* A, const bf16_t* Bt, int nN, int K, const EpiS& E) {
;     ...
;         __syncthreads();
;         LAS float* part = (LAS float*)(lds + w * 8192);
; #pragma unroll
;         for (int r = 0; r < 16; ++r) { const int row = (r & 3) + 8 * (r >> 2) + 4 * h; part[row * 64 + r32] = c0[r]; part[row * 64 + 32 + r32] = c1[r]; }
;         __syncthreads();
;         f32x4 v = (f32x4){0.f, 0.f, 0.f, 0.f};
; #pragma unroll
;         for (int ww = 0; ww < 8; ++ww) v += *(const LAS f32x4*)(lds + ww * 8192 + (tid >> 4) * 256 + (tid & 15) * 16);
;         E(v, MP + rb * 32 + (tid >> 4), pn, wc, (tid >> 3) & 1, 4 * (tid & 7));
	s_nop 11
	ds_write2_b32 v45, v2, v18 offset1:32
	ds_write2_b32 v45, v3, v19 offset0:64 offset1:96
	ds_write2_b32 v45, v4, v20 offset0:128 offset1:160
	ds_write2_b32 v45, v5, v21 offset0:192 offset1:224
	ds_write2_b32 v48, v6, v22 offset1:32
	ds_write2_b32 v48, v7, v23 offset0:64 offset1:96
	ds_write2_b32 v48, v8, v24 offset0:128 offset1:160
	ds_write2_b32 v48, v9, v25 offset0:192 offset1:224
	ds_write2_b32 v49, v10, v26 offset1:32
	ds_write2_b32 v49, v11, v27 offset0:64 offset1:96
	ds_write2_b32 v49, v12, v28 offset0:128 offset1:160
	ds_write2_b32 v49, v13, v29 offset0:192 offset1:224
	ds_write2_b32 v50, v14, v30 offset1:32
	ds_write2_b32 v50, v15, v31 offset0:64 offset1:96
	ds_write2_b32 v50, v16, v32 offset0:128 offset1:160
	ds_write2_b32 v50, v17, v33 offset0:192 offset1:224
	s_waitcnt lgkmcnt(0)
	s_barrier
	ds_read_b128 v[2:5], v46
	ds_read_b128 v[6:9], v46 offset:8192
	ds_read_b128 v[10:13], v46 offset:16384
	ds_read_b128 v[14:17], v46 offset:24576
	ds_read_b128 v[18:21], v46 offset:32768
	ds_read_b128 v[22:25], v46 offset:40960
	ds_read_b128 v[26:29], v46 offset:49152
	ds_read_b128 v[30:33], v46 offset:57344
	s_waitcnt lgkmcnt(7)
	v_pk_add_f32 v[2:3], v[2:3], 0 op_sel_hi:[1,0]
	v_pk_add_f32 v[4:5], v[4:5], 0 op_sel_hi:[1,0]
	s_waitcnt lgkmcnt(6)
	v_pk_add_f32 v[2:3], v[2:3], v[6:7]
	v_pk_add_f32 v[4:5], v[4:5], v[8:9]
	s_waitcnt lgkmcnt(5)
	v_pk_add_f32 v[2:3], v[2:3], v[10:11]
	v_pk_add_f32 v[4:5], v[4:5], v[12:13]
	s_waitcnt lgkmcnt(4)
	v_pk_add_f32 v[2:3], v[2:3], v[14:15]
	v_pk_add_f32 v[4:5], v[4:5], v[16:17]
	s_waitcnt lgkmcnt(3)
	v_pk_add_f32 v[2:3], v[2:3], v[18:19]
	v_pk_add_f32 v[4:5], v[4:5], v[20:21]
	s_waitcnt lgkmcnt(2)
	v_pk_add_f32 v[2:3], v[2:3], v[22:23]
	v_pk_add_f32 v[4:5], v[4:5], v[24:25]
	s_waitcnt lgkmcnt(1)
	v_pk_add_f32 v[2:3], v[2:3], v[26:27]
	v_pk_add_f32 v[4:5], v[4:5], v[28:29]
	s_waitcnt lgkmcnt(0)
	v_pk_add_f32 v[2:3], v[2:3], v[30:31]
	v_pk_add_f32 v[4:5], v[4:5], v[32:33]
	s_waitcnt vmcnt(0)
	v_fmamk_f32 v6, v34, 0x3a800000, v47
	v_mul_f32_e32 v7, 0x4b800000, v6
	v_cmp_gt_f32_e32 vcc, s68, v6
	s_nop 1
	v_cndmask_b32_e32 v6, v6, v7, vcc
	v_rsq_f32_e32 v6, v6
	s_nop 0
	v_mul_f32_e32 v7, 0x45800000, v6
	v_cndmask_b32_e32 v6, v6, v7, vcc
	v_pk_mul_f32 v[2:3], v[2:3], v[6:7] op_sel_hi:[1,0]
	v_pk_mul_f32 v[4:5], v[4:5], v[6:7] op_sel_hi:[1,0]
	ds_bpermute_b32 v6, v44, v2
	ds_bpermute_b32 v7, v44, v3
	ds_bpermute_b32 v8, v44, v4
	ds_bpermute_b32 v9, v44, v5
	s_cbranch_scc0 .LBB0_342
	v_lshlrev_b32_e32 v34, 10, v41
	v_lshl_add_u64 v[12:13], s[10:11], 0, v[34:35]
	v_lshl_add_u64 v[12:13], s[4:5], 1, v[12:13]
	v_cvt_pk_bf16_f32 v10, v2, v3
	v_cvt_pk_bf16_f32 v11, v4, v5
	v_lshl_add_u64 v[12:13], v[12:13], 0, s[26:27]
	s_mov_b64 s[50:51], -1
	s_cbranch_execz .LBB0_343
	v_mov_b32_e32 v34, v43
	s_and_saveexec_b64 s[62:63], s[50:51]
	s_cbranch_execz .LBB0_338
	s_branch .LBB0_350

;     DI void operator()(const f32x4 v, int row, int pn, int wc, int bj, int cl) const {
;     ...
;         if (MODE == 0) x = *(const f32x4*)(xin + (size_t)row * D + col);
; template <class EpiS>
; DI void sample_gemm(LAS unsigned char* lds, const bf16_t* A, const bf16_t* Bt, int nN, int K, const EpiS& E) {
;     ...
;     for (int un = (int)blockIdx.x; un < nunits; un += (int)gridDim.x) {
;         const int rb = un & 3, wc = (un >> 2) & 3, pn = un >> 4;
;         const bf16_t* ap = A + (size_t)(MP + rb * 32 + r32) * K + w * kw + h * 8;
;         const bf16_t* b0p = Bt + (size_t)(pn * 256 + wc * 32 + r32) * K + w * kw + h * 8;
;         const bf16_t* b1p = b0p + (size_t)128 * K;
;         f32x16 c0, c1;
; #pragma unroll
;         for (int r = 0; r < 16; ++r) { c0[r] = 0.f; c1[r] = 0.f; }
; #pragma unroll 8
;         for (int ks = 0; ks < nk; ++ks) {
;             const bf16x8 a = *(const bf16x8*)(ap + ks * 16), b0 = *(const bf16x8*)(b0p + ks * 16), b1 = *(const bf16x8*)(b1p + ks * 16);
;             c0 = __builtin_amdgcn_mfma_f32_32x32x16_bf16(a, b0, c0, 0, 0, 0);
;             c1 = __builtin_amdgcn_mfma_f32_32x32x16_bf16(a, b1, c1, 0, 0, 0);
;         }
.LBB0_546:
	s_and_b32 s0, s14, 0x60
	s_or_b32 s18, s0, 0x8000
	s_waitcnt lgkmcnt(0)
	v_or_b32_e32 v3, s18, v40
	s_and_b32 s0, s12, 0xffffff00
	s_and_b32 s1, s10, 0x60
	v_lshlrev_b32_e32 v34, 11, v3
	s_or_b32 s19, s0, s1
	v_lshl_add_u64 v[76:77], v[36:37], 0, v[34:35]
	v_or_b32_e32 v2, s19, v40
	v_ashrrev_i32_e32 v3, 31, v2
	v_lshlrev_b64 v[2:3], 11, v[2:3]
	v_lshl_add_u64 v[78:79], v[38:39], 0, v[2:3]
	v_add_co_u32_e64 v80, s[0:1], s16, v78
	v_add_u32_e32 v51, s18, v1
	s_nop 0
	v_addc_co_u32_e64 v81, s[0:1], 0, v79, s[0:1]
	v_lshlrev_b32_e32 v34, 12, v51
	v_or_b32_e32 v60, s19, v41
	v_ashrrev_i32_e32 v61, 31, v60
	v_lshl_add_u64 v[56:57], s[4:5], 0, v[34:35]
	v_lshl_add_u64 v[56:57], v[60:61], 2, v[56:57]
	v_lshlrev_b32_e32 v34, 11, v51
	global_load_dwordx4 v[240:243], v[56:57], off
	v_lshl_add_u64 v[158:159], v[76:77], 0, v[182:183]
	v_lshl_add_u64 v[160:161], v[78:79], 0, v[182:183]
	v_lshl_add_u64 v[180:181], v[80:81], 0, v[182:183]
	global_load_dwordx4 v[82:85], v[158:159], off
	v_lshl_add_u64 v[158:159], v[158:159], 0, s[80:81]
	global_load_dwordx4 v[86:89], v[158:159], off
	v_lshl_add_u64 v[158:159], v[158:159], 0, s[80:81]
	global_load_dwordx4 v[90:93], v[158:159], off
	v_lshl_add_u64 v[158:159], v[158:159], 0, s[80:81]
	global_load_dwordx4 v[94:97], v[158:159], off
	v_lshl_add_u64 v[158:159], v[158:159], 0, s[82:83]
	global_load_dwordx4 v[98:101], v[160:161], off
	v_lshl_add_u64 v[160:161], v[160:161], 0, s[80:81]
	global_load_dwordx4 v[102:105], v[160:161], off
	v_lshl_add_u64 v[160:161], v[160:161], 0, s[80:81]
	global_load_dwordx4 v[106:109], v[160:161], off
	v_lshl_add_u64 v[160:161], v[160:161], 0, s[80:81]
	global_load_dwordx4 v[110:113], v[160:161], off
	v_lshl_add_u64 v[160:161], v[160:161], 0, s[82:83]
	global_load_dwordx4 v[132:135], v[180:181], off
	v_lshl_add_u64 v[180:181], v[180:181], 0, s[80:81]
	global_load_dwordx4 v[136:139], v[180:181], off
	v_lshl_add_u64 v[180:181], v[180:181], 0, s[80:81]
	global_load_dwordx4 v[140:143], v[180:181], off
	v_lshl_add_u64 v[180:181], v[180:181], 0, s[80:81]
	global_load_dwordx4 v[144:147], v[180:181], off
	v_lshl_add_u64 v[180:181], v[180:181], 0, s[82:83]
	global_load_dwordx4 v[148:151], v[158:159], off offset:128
	v_lshl_add_u64 v[158:159], v[158:159], 0, s[80:81]
	global_load_dwordx4 v[166:169], v[158:159], off offset:128
	v_lshl_add_u64 v[158:159], v[158:159], 0, s[80:81]
	global_load_dwordx4 v[170:173], v[158:159], off offset:128
	v_lshl_add_u64 v[158:159], v[158:159], 0, s[80:81]
	global_load_dwordx4 v[174:177], v[158:159], off offset:128
	global_load_dwordx4 v[198:201], v[160:161], off offset:128
	v_lshl_add_u64 v[160:161], v[160:161], 0, s[80:81]
	global_load_dwordx4 v[202:205], v[160:161], off offset:128
	v_lshl_add_u64 v[160:161], v[160:161], 0, s[80:81]
	global_load_dwordx4 v[216:219], v[160:161], off offset:128
	v_lshl_add_u64 v[160:161], v[160:161], 0, s[80:81]
	global_load_dwordx4 v[220:223], v[160:161], off offset:128
	global_load_dwordx4 v[224:227], v[180:181], off offset:128
	v_lshl_add_u64 v[180:181], v[180:181], 0, s[80:81]
	global_load_dwordx4 v[228:231], v[180:181], off offset:128
	v_lshl_add_u64 v[180:181], v[180:181], 0, s[80:81]
	global_load_dwordx4 v[232:235], v[180:181], off offset:128
	v_lshl_add_u64 v[180:181], v[180:181], 0, s[80:81]
	global_load_dwordx4 v[236:239], v[180:181], off offset:128
	s_waitcnt vmcnt(16)
	ds_write_b128 v194, v[82:85]
	ds_write_b128 v195, v[86:89] offset:1024
	ds_write_b128 v194, v[90:93] offset:2048
	ds_write_b128 v195, v[94:97] offset:3072
	ds_write_b128 v194, v[98:101] offset:4096
	ds_write_b128 v195, v[102:105] offset:5120
	ds_write_b128 v194, v[106:109] offset:6144
	ds_write_b128 v195, v[110:113] offset:7168
	ds_read_b128 v[82:85], v244
	ds_read_b128 v[86:89], v245
	ds_read_b128 v[90:93], v246
	ds_read_b128 v[94:97], v193
	ds_read_b128 v[98:101], v244 offset:4096
	ds_read_b128 v[102:105], v245 offset:4096
	ds_read_b128 v[106:109], v246 offset:4096
	ds_read_b128 v[110:113], v193 offset:4096
	s_waitcnt lgkmcnt(0)
	v_mfma_f32_32x32x16_bf16 v[2:17], v[82:85], v[98:101], 0
	v_mfma_f32_32x32x16_bf16 v[2:17], v[86:89], v[102:105], v[2:17]
	v_mfma_f32_32x32x16_bf16 v[2:17], v[90:93], v[106:109], v[2:17]
	v_mfma_f32_32x32x16_bf16 v[2:17], v[94:97], v[110:113], v[2:17]
	s_waitcnt vmcnt(12)
	ds_write_b128 v194, v[132:135] offset:4096
	ds_write_b128 v195, v[136:139] offset:5120
	ds_write_b128 v194, v[140:143] offset:6144
	ds_write_b128 v195, v[144:147] offset:7168
	ds_read_b128 v[132:135], v244 offset:4096
	ds_read_b128 v[136:139], v245 offset:4096
	ds_read_b128 v[140:143], v246 offset:4096
	ds_read_b128 v[144:147], v193 offset:4096
	s_waitcnt lgkmcnt(0)
	v_mfma_f32_32x32x16_bf16 v[18:33], v[82:85], v[132:135], 0
	v_mfma_f32_32x32x16_bf16 v[18:33], v[86:89], v[136:139], v[18:33]
	v_mfma_f32_32x32x16_bf16 v[18:33], v[90:93], v[140:143], v[18:33]
	v_mfma_f32_32x32x16_bf16 v[18:33], v[94:97], v[144:147], v[18:33]
	s_waitcnt vmcnt(4)
	ds_write_b128 v194, v[148:151]
	ds_write_b128 v195, v[166:169] offset:1024
	ds_write_b128 v194, v[170:173] offset:2048
	ds_write_b128 v195, v[174:177] offset:3072
	ds_write_b128 v194, v[198:201] offset:4096
	ds_write_b128 v195, v[202:205] offset:5120
	ds_write_b128 v194, v[216:219] offset:6144
	ds_write_b128 v195, v[220:223] offset:7168
	ds_read_b128 v[148:151], v244
	ds_read_b128 v[166:169], v245
	ds_read_b128 v[170:173], v246
	ds_read_b128 v[174:177], v193
	ds_read_b128 v[198:201], v244 offset:4096
	ds_read_b128 v[202:205], v245 offset:4096
	ds_read_b128 v[216:219], v246 offset:4096
	ds_read_b128 v[220:223], v193 offset:4096
	s_waitcnt lgkmcnt(0)
	v_mfma_f32_32x32x16_bf16 v[2:17], v[148:151], v[198:201], v[2:17]
	v_mfma_f32_32x32x16_bf16 v[2:17], v[166:169], v[202:205], v[2:17]
	v_mfma_f32_32x32x16_bf16 v[2:17], v[170:173], v[216:219], v[2:17]
	v_mfma_f32_32x32x16_bf16 v[2:17], v[174:177], v[220:223], v[2:17]
	s_waitcnt vmcnt(0)
	ds_write_b128 v194, v[224:227] offset:4096
	ds_write_b128 v195, v[228:231] offset:5120
	ds_write_b128 v194, v[232:235] offset:6144
	ds_write_b128 v195, v[236:239] offset:7168
	ds_read_b128 v[224:227], v244 offset:4096
	ds_read_b128 v[228:231], v245 offset:4096
	ds_read_b128 v[232:235], v246 offset:4096
	ds_read_b128 v[236:239], v193 offset:4096
	s_waitcnt lgkmcnt(0)
	v_mfma_f32_32x32x16_bf16 v[18:33], v[148:151], v[224:227], v[18:33]
	v_mfma_f32_32x32x16_bf16 v[18:33], v[166:169], v[228:231], v[18:33]
	v_mfma_f32_32x32x16_bf16 v[18:33], v[170:173], v[232:235], v[18:33]
	v_mfma_f32_32x32x16_bf16 v[18:33], v[174:177], v[236:239], v[18:33]
	s_barrier
; #define LAS __attribute__((address_space(3)))
; DI float bflo(unsigned u) { return __uint_as_float(u << 16); }
; DI float bfhi(unsigned u) { return __uint_as_float(u & 0xffff0000u); }
; DI float red16(float v) { v += __shfl_xor(v, 1); v += __shfl_xor(v, 2); v += __shfl_xor(v, 4); v += __shfl_xor(v, 8); return v; }
; DI u32x2 pk4(const f32x4 a) { return (u32x2){pk2(a[0], a[1]), pk2(a[2], a[3])}; }
;     DI void operator()(const f32x4 v, int row, int pn, int wc, int bj, int cl) const {
;     ...
;         if (MODE == 0) x = *(const f32x4*)(xin + (size_t)row * D + col);
;         else { const u32x2 w = *(const u32x2*)(XN + (size_t)row * D + col); x = (f32x4){bflo(w.x), bfhi(w.x), bflo(w.y), bfhi(w.y)}; }
;         x += v;
;         if (MODE == 2) *(f32x4*)(out + (size_t)row * D + col) = x;
;         else {
;             *(u32x2*)(XN + (size_t)row * D + col) = pk4(x);
;             const float ssq = red16((x[0] * x[0] + x[1] * x[1]) + (x[2] * x[2] + x[3] * x[3]));
;             if ((threadIdx.x & 15) == 0) atomicAdd(SS + row, ssq);
;         }
; template <class EpiS>
; DI void sample_gemm(LAS unsigned char* lds, const bf16_t* A, const bf16_t* Bt, int nN, int K, const EpiS& E) {
;     ...
;         __syncthreads();
;         LAS float* part = (LAS float*)(lds + w * 8192);
; #pragma unroll
;         for (int r = 0; r < 16; ++r) { const int row = (r & 3) + 8 * (r >> 2) + 4 * h; part[row * 64 + r32] = c0[r]; part[row * 64 + 32 + r32] = c1[r]; }
;         __syncthreads();
;         f32x4 v = (f32x4){0.f, 0.f, 0.f, 0.f};
; #pragma unroll
;         for (int ww = 0; ww < 8; ++ww) v += *(const LAS f32x4*)(lds + ww * 8192 + (tid >> 4) * 256 + (tid & 15) * 16);
;         E(v, MP + rb * 32 + (tid >> 4), pn, wc, (tid >> 3) & 1, 4 * (tid & 7));
	s_nop 11
	ds_write2_b32 v46, v2, v18 offset1:32
	ds_write2_b32 v46, v3, v19 offset0:64 offset1:96
	ds_write2_b32 v46, v4, v20 offset0:128 offset1:160
	ds_write2_b32 v46, v5, v21 offset0:192 offset1:224
	ds_write2_b32 v48, v6, v22 offset1:32
	ds_write2_b32 v48, v7, v23 offset0:64 offset1:96
	ds_write2_b32 v48, v8, v24 offset0:128 offset1:160
	ds_write2_b32 v48, v9, v25 offset0:192 offset1:224
	ds_write2_b32 v49, v10, v26 offset1:32
	ds_write2_b32 v49, v11, v27 offset0:64 offset1:96
	ds_write2_b32 v49, v12, v28 offset0:128 offset1:160
	ds_write2_b32 v49, v13, v29 offset0:192 offset1:224
	ds_write2_b32 v50, v14, v30 offset1:32
	ds_write2_b32 v50, v15, v31 offset0:64 offset1:96
	ds_write2_b32 v50, v16, v32 offset0:128 offset1:160
	ds_write2_b32 v50, v17, v33 offset0:192 offset1:224
	s_waitcnt lgkmcnt(0)
	s_barrier
	ds_read_b128 v[6:9], v47
	ds_read_b128 v[10:13], v47 offset:8192
	ds_read_b128 v[14:17], v47 offset:16384
	ds_read_b128 v[18:21], v47 offset:24576
	ds_read_b128 v[22:25], v47 offset:32768
	ds_read_b128 v[26:29], v47 offset:40960
	ds_read_b128 v[30:33], v47 offset:49152
	ds_read_b128 v[52:55], v47 offset:57344
	s_waitcnt lgkmcnt(7)
	v_pk_add_f32 v[8:9], v[8:9], 0 op_sel_hi:[1,0]
	v_pk_add_f32 v[6:7], v[6:7], 0 op_sel_hi:[1,0]
	s_waitcnt lgkmcnt(6)
	v_pk_add_f32 v[8:9], v[8:9], v[12:13]
	v_pk_add_f32 v[6:7], v[6:7], v[10:11]
	s_waitcnt lgkmcnt(5)
	v_pk_add_f32 v[8:9], v[8:9], v[16:17]
	v_pk_add_f32 v[6:7], v[6:7], v[14:15]
	s_waitcnt lgkmcnt(4)
	v_pk_add_f32 v[8:9], v[8:9], v[20:21]
	v_pk_add_f32 v[6:7], v[6:7], v[18:19]
	s_waitcnt lgkmcnt(3)
	v_pk_add_f32 v[8:9], v[8:9], v[24:25]
	v_pk_add_f32 v[6:7], v[6:7], v[22:23]
	s_waitcnt lgkmcnt(2)
	v_pk_add_f32 v[8:9], v[8:9], v[28:29]
	v_pk_add_f32 v[6:7], v[6:7], v[26:27]
	s_waitcnt lgkmcnt(1)
	v_pk_add_f32 v[8:9], v[8:9], v[32:33]
	v_pk_add_f32 v[6:7], v[6:7], v[30:31]
	s_waitcnt lgkmcnt(0)
	v_pk_add_f32 v[8:9], v[8:9], v[54:55]
	v_pk_add_f32 v[6:7], v[6:7], v[52:53]
	s_waitcnt vmcnt(0)
	v_pk_add_f32 v[4:5], v[8:9], v[242:243]
	v_pk_add_f32 v[2:3], v[6:7], v[240:241]
	v_mul_f32_e32 v7, v5, v5
	v_mul_f32_e32 v6, v3, v3
	v_fmac_f32_e32 v6, v2, v2
	v_fmac_f32_e32 v7, v4, v4
	v_add_f32_e32 v6, v6, v7
	ds_bpermute_b32 v7, v42, v6
	s_waitcnt lgkmcnt(0)
	v_add_f32_e32 v6, v6, v7
	ds_bpermute_b32 v7, v43, v6
	s_waitcnt lgkmcnt(0)
	v_add_f32_e32 v8, v6, v7
	ds_bpermute_b32 v9, v44, v8
	v_cvt_pk_bf16_f32 v6, v2, v3
	v_cvt_pk_bf16_f32 v7, v4, v5
	v_lshl_add_u64 v[4:5], s[34:35], 0, v[34:35]
	v_lshl_add_u64 v[4:5], v[60:61], 1, v[4:5]
	s_waitcnt lgkmcnt(0)
	v_add_f32_e32 v2, v8, v9
	ds_bpermute_b32 v3, v45, v2
	global_store_dwordx2 v[4:5], v[6:7], off
	s_and_saveexec_b64 s[0:1], vcc
	s_cbranch_execz .LBB0_545
	v_lshlrev_b32_e32 v4, 2, v51
	s_waitcnt lgkmcnt(0)
	v_add_f32_e32 v2, v2, v3
	global_atomic_add_f32 v4, v2, s[8:9]
	s_branch .LBB0_545

; DI float row_rstd(const float* SS, int row) { return rsqrtf(SS[row] * (1.0f / 1024.0f) + 1e-6f); }
;     DI void operator()(const f32x4 v, int row, int pn, int wc, int bj, int cl) const {
;         const float rs = row_rstd(SS, row);
; template <class EpiS>
; DI void sample_gemm(LAS unsigned char* lds, const bf16_t* A, const bf16_t* Bt, int nN, int K, const EpiS& E) {
;     ...
;     for (int un = (int)blockIdx.x; un < nunits; un += (int)gridDim.x) {
;         const int rb = un & 3, wc = (un >> 2) & 3, pn = un >> 4;
;         const bf16_t* ap = A + (size_t)(MP + rb * 32 + r32) * K + w * kw + h * 8;
;         const bf16_t* b0p = Bt + (size_t)(pn * 256 + wc * 32 + r32) * K + w * kw + h * 8;
;         const bf16_t* b1p = b0p + (size_t)128 * K;
;         f32x16 c0, c1;
; #pragma unroll
;         for (int r = 0; r < 16; ++r) { c0[r] = 0.f; c1[r] = 0.f; }
; #pragma unroll 8
;         for (int ks = 0; ks < nk; ++ks) {
;             const bf16x8 a = *(const bf16x8*)(ap + ks * 16), b0 = *(const bf16x8*)(b0p + ks * 16), b1 = *(const bf16x8*)(b1p + ks * 16);
;             c0 = __builtin_amdgcn_mfma_f32_32x32x16_bf16(a, b0, c0, 0, 0, 0);
;             c1 = __builtin_amdgcn_mfma_f32_32x32x16_bf16(a, b1, c1, 0, 0, 0);
;         }
.LBB0_619:
	s_and_b32 s16, s10, 0x60
	s_bitset1_b32 s16, 15
	s_ashr_i32 s4, s14, 4
	s_waitcnt lgkmcnt(2)
	v_or_b32_e32 v3, s16, v42
	s_lshl_b32 s0, s4, 8
	s_and_b32 s15, s8, 0x60
	v_lshlrev_b32_e32 v34, 11, v3
	s_or_b32 s0, s0, s15
	v_lshl_add_u64 v[76:77], v[36:37], 0, v[34:35]
	v_or_b32_e32 v2, s0, v42
	v_ashrrev_i32_e32 v3, 31, v2
	v_lshlrev_b64 v[2:3], 11, v[2:3]
	v_lshl_add_u64 v[78:79], v[38:39], 0, v[2:3]
	s_waitcnt lgkmcnt(0)
	v_add_co_u32_e64 v80, s[0:1], s12, v78
	v_addc_co_u32_e64 v81, s[0:1], 0, v79, s[0:1]
	v_add_u32_e32 v240, s16, v43
	v_lshlrev_b32_e32 v240, 2, v240
	global_load_dword v240, v240, s[50:51]
	v_lshl_add_u64 v[158:159], v[76:77], 0, v[182:183]
	v_lshl_add_u64 v[160:161], v[78:79], 0, v[182:183]
	v_lshl_add_u64 v[180:181], v[80:81], 0, v[182:183]
	global_load_dwordx4 v[82:85], v[158:159], off
	v_lshl_add_u64 v[158:159], v[158:159], 0, s[80:81]
	global_load_dwordx4 v[86:89], v[158:159], off
	v_lshl_add_u64 v[158:159], v[158:159], 0, s[80:81]
	global_load_dwordx4 v[90:93], v[158:159], off
	v_lshl_add_u64 v[158:159], v[158:159], 0, s[80:81]
	global_load_dwordx4 v[94:97], v[158:159], off
	v_lshl_add_u64 v[158:159], v[158:159], 0, s[82:83]
	global_load_dwordx4 v[98:101], v[160:161], off
	v_lshl_add_u64 v[160:161], v[160:161], 0, s[80:81]
	global_load_dwordx4 v[102:105], v[160:161], off
	v_lshl_add_u64 v[160:161], v[160:161], 0, s[80:81]
	global_load_dwordx4 v[106:109], v[160:161], off
	v_lshl_add_u64 v[160:161], v[160:161], 0, s[80:81]
	global_load_dwordx4 v[110:113], v[160:161], off
	v_lshl_add_u64 v[160:161], v[160:161], 0, s[82:83]
	global_load_dwordx4 v[132:135], v[180:181], off
	v_lshl_add_u64 v[180:181], v[180:181], 0, s[80:81]
	global_load_dwordx4 v[136:139], v[180:181], off
	v_lshl_add_u64 v[180:181], v[180:181], 0, s[80:81]
	global_load_dwordx4 v[140:143], v[180:181], off
	v_lshl_add_u64 v[180:181], v[180:181], 0, s[80:81]
	global_load_dwordx4 v[144:147], v[180:181], off
	v_lshl_add_u64 v[180:181], v[180:181], 0, s[82:83]
	global_load_dwordx4 v[148:151], v[158:159], off offset:128
	v_lshl_add_u64 v[158:159], v[158:159], 0, s[80:81]
	global_load_dwordx4 v[166:169], v[158:159], off offset:128
	v_lshl_add_u64 v[158:159], v[158:159], 0, s[80:81]
	global_load_dwordx4 v[170:173], v[158:159], off offset:128
	v_lshl_add_u64 v[158:159], v[158:159], 0, s[80:81]
	global_load_dwordx4 v[174:177], v[158:159], off offset:128
	global_load_dwordx4 v[198:201], v[160:161], off offset:128
	v_lshl_add_u64 v[160:161], v[160:161], 0, s[80:81]
	global_load_dwordx4 v[202:205], v[160:161], off offset:128
	v_lshl_add_u64 v[160:161], v[160:161], 0, s[80:81]
	global_load_dwordx4 v[216:219], v[160:161], off offset:128
	v_lshl_add_u64 v[160:161], v[160:161], 0, s[80:81]
	global_load_dwordx4 v[220:223], v[160:161], off offset:128
	global_load_dwordx4 v[224:227], v[180:181], off offset:128
	v_lshl_add_u64 v[180:181], v[180:181], 0, s[80:81]
	global_load_dwordx4 v[228:231], v[180:181], off offset:128
	v_lshl_add_u64 v[180:181], v[180:181], 0, s[80:81]
	global_load_dwordx4 v[232:235], v[180:181], off offset:128
	v_lshl_add_u64 v[180:181], v[180:181], 0, s[80:81]
	global_load_dwordx4 v[236:239], v[180:181], off offset:128
	s_waitcnt vmcnt(16)
	ds_write_b128 v194, v[82:85]
	ds_write_b128 v195, v[86:89] offset:1024
	ds_write_b128 v194, v[90:93] offset:2048
	ds_write_b128 v195, v[94:97] offset:3072
	ds_write_b128 v194, v[98:101] offset:4096
	ds_write_b128 v195, v[102:105] offset:5120
	ds_write_b128 v194, v[106:109] offset:6144
	ds_write_b128 v195, v[110:113] offset:7168
	ds_read_b128 v[82:85], v244
	ds_read_b128 v[86:89], v245
	ds_read_b128 v[90:93], v246
	ds_read_b128 v[94:97], v193
	ds_read_b128 v[98:101], v244 offset:4096
	ds_read_b128 v[102:105], v245 offset:4096
	ds_read_b128 v[106:109], v246 offset:4096
	ds_read_b128 v[110:113], v193 offset:4096
	s_waitcnt lgkmcnt(0)
	v_mfma_f32_32x32x16_bf16 v[2:17], v[82:85], v[98:101], 0
	v_mfma_f32_32x32x16_bf16 v[2:17], v[86:89], v[102:105], v[2:17]
	v_mfma_f32_32x32x16_bf16 v[2:17], v[90:93], v[106:109], v[2:17]
	v_mfma_f32_32x32x16_bf16 v[2:17], v[94:97], v[110:113], v[2:17]
	s_waitcnt vmcnt(12)
	ds_write_b128 v194, v[132:135] offset:4096
	ds_write_b128 v195, v[136:139] offset:5120
	ds_write_b128 v194, v[140:143] offset:6144
	ds_write_b128 v195, v[144:147] offset:7168
	ds_read_b128 v[132:135], v244 offset:4096
	ds_read_b128 v[136:139], v245 offset:4096
	ds_read_b128 v[140:143], v246 offset:4096
	ds_read_b128 v[144:147], v193 offset:4096
	s_waitcnt lgkmcnt(0)
	v_mfma_f32_32x32x16_bf16 v[18:33], v[82:85], v[132:135], 0
	v_mfma_f32_32x32x16_bf16 v[18:33], v[86:89], v[136:139], v[18:33]
	v_mfma_f32_32x32x16_bf16 v[18:33], v[90:93], v[140:143], v[18:33]
	v_mfma_f32_32x32x16_bf16 v[18:33], v[94:97], v[144:147], v[18:33]
	s_waitcnt vmcnt(4)
	ds_write_b128 v194, v[148:151]
	ds_write_b128 v195, v[166:169] offset:1024
	ds_write_b128 v194, v[170:173] offset:2048
	ds_write_b128 v195, v[174:177] offset:3072
	ds_write_b128 v194, v[198:201] offset:4096
	ds_write_b128 v195, v[202:205] offset:5120
	ds_write_b128 v194, v[216:219] offset:6144
	ds_write_b128 v195, v[220:223] offset:7168
	ds_read_b128 v[148:151], v244
	ds_read_b128 v[166:169], v245
	ds_read_b128 v[170:173], v246
	ds_read_b128 v[174:177], v193
	ds_read_b128 v[198:201], v244 offset:4096
	ds_read_b128 v[202:205], v245 offset:4096
	ds_read_b128 v[216:219], v246 offset:4096
	ds_read_b128 v[220:223], v193 offset:4096
	s_waitcnt lgkmcnt(0)
	v_mfma_f32_32x32x16_bf16 v[2:17], v[148:151], v[198:201], v[2:17]
	v_mfma_f32_32x32x16_bf16 v[2:17], v[166:169], v[202:205], v[2:17]
	v_mfma_f32_32x32x16_bf16 v[2:17], v[170:173], v[216:219], v[2:17]
	v_mfma_f32_32x32x16_bf16 v[2:17], v[174:177], v[220:223], v[2:17]
	s_waitcnt vmcnt(0)
	ds_write_b128 v194, v[224:227] offset:4096
	ds_write_b128 v195, v[228:231] offset:5120
	ds_write_b128 v194, v[232:235] offset:6144
	ds_write_b128 v195, v[236:239] offset:7168
	ds_read_b128 v[224:227], v244 offset:4096
	ds_read_b128 v[228:231], v245 offset:4096
	ds_read_b128 v[232:235], v246 offset:4096
	ds_read_b128 v[236:239], v193 offset:4096
	s_waitcnt lgkmcnt(0)
	v_mfma_f32_32x32x16_bf16 v[18:33], v[148:151], v[224:227], v[18:33]
	v_mfma_f32_32x32x16_bf16 v[18:33], v[166:169], v[228:231], v[18:33]
	v_mfma_f32_32x32x16_bf16 v[18:33], v[170:173], v[232:235], v[18:33]
	v_mfma_f32_32x32x16_bf16 v[18:33], v[174:177], v[236:239], v[18:33]
	s_barrier
; #define LAS __attribute__((address_space(3)))
; DI float sigmoidf_(float x) { return __builtin_amdgcn_rcpf(1.0f + __expf(-x)); }
; DI float row_rstd(const float* SS, int row) { return rsqrtf(SS[row] * (1.0f / 1024.0f) + 1e-6f); }
; DI f32x4 shx8(const f32x4 v) { f32x4 o; o[0] = __shfl_xor(v[0], 8); o[1] = __shfl_xor(v[1], 8); o[2] = __shfl_xor(v[2], 8); o[3] = __shfl_xor(v[3], 8); return o; }
; DI u32x2 pk4(const f32x4 a) { return (u32x2){pk2(a[0], a[1]), pk2(a[2], a[3])}; }
;     DI void operator()(const f32x4 v, int row, int pn, int wc, int bj, int cl) const {
;         const float rs = row_rstd(SS, row);
;         const f32x4 o = shx8(v);
;         if (bj == 0) {
;             f32x4 hv;
; #pragma unroll
;             for (int i = 0; i < 4; ++i) { const float g0 = v[i] * rs; hv[i] = g0 * sigmoidf_(g0) * (o[i] * rs); }
;             *(u32x2*)(HID + (size_t)row * FH + pn * 128 + wc * 32 + cl) = pk4(hv);
; template <class EpiS>
; DI void sample_gemm(LAS unsigned char* lds, const bf16_t* A, const bf16_t* Bt, int nN, int K, const EpiS& E) {
;     ...
;         __syncthreads();
;         LAS float* part = (LAS float*)(lds + w * 8192);
; #pragma unroll
;         for (int r = 0; r < 16; ++r) { const int row = (r & 3) + 8 * (r >> 2) + 4 * h; part[row * 64 + r32] = c0[r]; part[row * 64 + 32 + r32] = c1[r]; }
;         __syncthreads();
;         f32x4 v = (f32x4){0.f, 0.f, 0.f, 0.f};
; #pragma unroll
;         for (int ww = 0; ww < 8; ++ww) v += *(const LAS f32x4*)(lds + ww * 8192 + (tid >> 4) * 256 + (tid & 15) * 16);
;         E(v, MP + rb * 32 + (tid >> 4), pn, wc, (tid >> 3) & 1, 4 * (tid & 7));
	s_nop 11
	ds_write2_b32 v45, v2, v18 offset1:32
	ds_write2_b32 v45, v3, v19 offset0:64 offset1:96
	ds_write2_b32 v45, v4, v20 offset0:128 offset1:160
	ds_write2_b32 v45, v5, v21 offset0:192 offset1:224
	ds_write2_b32 v48, v6, v22 offset1:32
	ds_write2_b32 v48, v7, v23 offset0:64 offset1:96
	ds_write2_b32 v48, v8, v24 offset0:128 offset1:160
	ds_write2_b32 v48, v9, v25 offset0:192 offset1:224
	ds_write2_b32 v49, v10, v26 offset1:32
	ds_write2_b32 v49, v11, v27 offset0:64 offset1:96
	ds_write2_b32 v49, v12, v28 offset0:128 offset1:160
	ds_write2_b32 v49, v13, v29 offset0:192 offset1:224
	ds_write2_b32 v50, v14, v30 offset1:32
	ds_write2_b32 v50, v15, v31 offset0:64 offset1:96
	ds_write2_b32 v50, v16, v32 offset0:128 offset1:160
	ds_write2_b32 v50, v17, v33 offset0:192 offset1:224
	s_waitcnt lgkmcnt(0)
	s_barrier
	ds_read_b128 v[2:5], v46
	ds_read_b128 v[6:9], v46 offset:8192
	ds_read_b128 v[10:13], v46 offset:16384
	ds_read_b128 v[14:17], v46 offset:24576
	ds_read_b128 v[18:21], v46 offset:32768
	ds_read_b128 v[22:25], v46 offset:40960
	ds_read_b128 v[26:29], v46 offset:49152
	ds_read_b128 v[30:33], v46 offset:57344
	s_waitcnt lgkmcnt(7)
	v_pk_add_f32 v[4:5], v[4:5], 0 op_sel_hi:[1,0]
	v_pk_add_f32 v[2:3], v[2:3], 0 op_sel_hi:[1,0]
	s_waitcnt lgkmcnt(6)
	v_pk_add_f32 v[4:5], v[4:5], v[8:9]
	v_pk_add_f32 v[2:3], v[2:3], v[6:7]
	s_waitcnt lgkmcnt(5)
	v_pk_add_f32 v[4:5], v[4:5], v[12:13]
	v_pk_add_f32 v[2:3], v[2:3], v[10:11]
	s_waitcnt lgkmcnt(4)
	v_pk_add_f32 v[4:5], v[4:5], v[16:17]
	v_pk_add_f32 v[2:3], v[2:3], v[14:15]
	s_waitcnt lgkmcnt(3)
	v_pk_add_f32 v[4:5], v[4:5], v[20:21]
	v_pk_add_f32 v[2:3], v[2:3], v[18:19]
	s_waitcnt lgkmcnt(2)
	v_pk_add_f32 v[4:5], v[4:5], v[24:25]
	v_pk_add_f32 v[2:3], v[2:3], v[22:23]
	s_waitcnt lgkmcnt(1)
	v_pk_add_f32 v[4:5], v[4:5], v[28:29]
	v_pk_add_f32 v[2:3], v[2:3], v[26:27]
	s_waitcnt lgkmcnt(0)
	v_pk_add_f32 v[6:7], v[4:5], v[32:33]
	v_pk_add_f32 v[8:9], v[2:3], v[30:31]
	ds_bpermute_b32 v2, v44, v8
	ds_bpermute_b32 v3, v44, v9
	ds_bpermute_b32 v4, v44, v6
	ds_bpermute_b32 v5, v44, v7
	s_and_saveexec_b64 s[6:7], vcc
	s_cbranch_execz .LBB0_618
	v_add_u32_e32 v10, s16, v43
	v_mul_u32_u24_e32 v10, 0xb00, v10
	v_lshlrev_b32_e32 v34, 1, v10
	s_lshl_b32 s16, s4, 7
	s_ashr_i32 s17, s16, 31
	s_lshl_b32 s4, s15, 1
	v_mov_b32_e32 v41, v35
	s_waitcnt vmcnt(0)
	v_fmamk_f32 v10, v240, 0x3a800000, v47
	v_mul_f32_e32 v11, 0x4b800000, v10
	v_cmp_gt_f32_e64 s[0:1], s13, v10
	s_nop 1
	v_cndmask_b32_e64 v10, v10, v11, s[0:1]
	v_rsq_f32_e32 v12, v10
	v_lshl_add_u64 v[10:11], s[24:25], 0, v[34:35]
	v_lshl_add_u64 v[10:11], s[16:17], 1, v[10:11]
	v_lshl_add_u64 v[10:11], v[10:11], 0, s[4:5]
	v_mul_f32_e32 v13, 0x45800000, v12
	v_cndmask_b32_e64 v12, v12, v13, s[0:1]
	v_pk_mul_f32 v[8:9], v[8:9], v[12:13] op_sel_hi:[1,0]
	v_pk_mul_f32 v[6:7], v[6:7], v[12:13] op_sel_hi:[1,0]
	v_mul_f32_e32 v13, 0xbfb8aa3b, v8
	v_mul_f32_e32 v14, 0xbfb8aa3b, v9
	v_mul_f32_e32 v15, 0xbfb8aa3b, v6
	v_mul_f32_e32 v16, 0xbfb8aa3b, v7
	v_exp_f32_e32 v13, v13
	v_exp_f32_e32 v14, v14
	v_exp_f32_e32 v15, v15
	v_exp_f32_e32 v16, v16
	v_add_f32_e32 v13, 1.0, v13
	v_add_f32_e32 v17, 1.0, v14
	v_add_f32_e32 v18, 1.0, v15
	v_add_f32_e32 v19, 1.0, v16
	v_rcp_f32_e32 v14, v13
	v_rcp_f32_e32 v15, v17
	v_rcp_f32_e32 v16, v18
	v_rcp_f32_e32 v17, v19
	s_waitcnt lgkmcnt(2)
	v_pk_mul_f32 v[2:3], v[12:13], v[2:3] op_sel_hi:[0,1]
	s_waitcnt lgkmcnt(0)
	v_pk_mul_f32 v[4:5], v[12:13], v[4:5] op_sel_hi:[0,1]
	v_pk_mul_f32 v[8:9], v[8:9], v[14:15]
	v_pk_mul_f32 v[6:7], v[6:7], v[16:17]
	v_pk_mul_f32 v[2:3], v[2:3], v[8:9]
	v_pk_mul_f32 v[4:5], v[4:5], v[6:7]
	v_cvt_pk_bf16_f32 v2, v2, v3
	v_cvt_pk_bf16_f32 v3, v4, v5
	v_lshl_add_u64 v[4:5], v[10:11], 0, v[40:41]
	global_store_dwordx2 v[4:5], v[2:3], off
	s_branch .LBB0_618

; DI float bflo(unsigned u) { return __uint_as_float(u << 16); }
; DI float bfhi(unsigned u) { return __uint_as_float(u & 0xffff0000u); }
;     DI void operator()(const f32x4 v, int row, int pn, int wc, int bj, int cl) const {
;     ...
;         else { const u32x2 w = *(const u32x2*)(XN + (size_t)row * D + col); x = (f32x4){bflo(w.x), bfhi(w.x), bflo(w.y), bfhi(w.y)}; }
; template <class EpiS>
; DI void sample_gemm(LAS unsigned char* lds, const bf16_t* A, const bf16_t* Bt, int nN, int K, const EpiS& E) {
;     ...
;     for (int un = (int)blockIdx.x; un < nunits; un += (int)gridDim.x) {
;         const int rb = un & 3, wc = (un >> 2) & 3, pn = un >> 4;
;         const bf16_t* ap = A + (size_t)(MP + rb * 32 + r32) * K + w * kw + h * 8;
;         const bf16_t* b0p = Bt + (size_t)(pn * 256 + wc * 32 + r32) * K + w * kw + h * 8;
;         const bf16_t* b1p = b0p + (size_t)128 * K;
;         f32x16 c0, c1;
; #pragma unroll
;         for (int r = 0; r < 16; ++r) { c0[r] = 0.f; c1[r] = 0.f; }
; #pragma unroll 8
;         for (int ks = 0; ks < nk; ++ks) {
;             const bf16x8 a = *(const bf16x8*)(ap + ks * 16), b0 = *(const bf16x8*)(b0p + ks * 16), b1 = *(const bf16x8*)(b1p + ks * 16);
;             c0 = __builtin_amdgcn_mfma_f32_32x32x16_bf16(a, b0, c0, 0, 0, 0);
;             c1 = __builtin_amdgcn_mfma_f32_32x32x16_bf16(a, b1, c1, 0, 0, 0);
;         }
.LBB0_722:
	s_and_b32 s17, s12, 0x60
	s_bitset1_b32 s17, 15
	v_or_b32_e32 v2, s17, v40
	v_mul_u32_u24_e32 v2, 0xb00, v2
	v_lshlrev_b32_e32 v34, 1, v2
	v_lshl_add_u64 v[76:77], v[36:37], 0, v[34:35]
	s_and_b32 s0, s6, 0xffffff00
	s_and_b32 s1, s4, 0x60
	s_or_b32 s18, s0, s1
	v_or_b32_e32 v2, s18, v40
	v_mad_i64_i32 v[78:79], s[0:1], v2, s14, v[38:39]
	s_waitcnt lgkmcnt(0)
	v_add_co_u32_e64 v80, s[0:1], s15, v78
	v_addc_co_u32_e64 v81, s[0:1], 0, v79, s[0:1]
	v_add_u32_e32 v210, s17, v188
	v_or_b32_e32 v212, s18, v42
	v_ashrrev_i32_e32 v213, 31, v212
	v_lshlrev_b32_e32 v214, 11, v210
	v_mov_b32_e32 v215, 0
	v_lshl_add_u64 v[206:207], s[34:35], 0, v[214:215]
	v_lshl_add_u64 v[206:207], v[212:213], 1, v[206:207]
	global_load_dwordx2 v[208:209], v[206:207], off
	v_lshl_add_u64 v[240:241], v[76:77], 0, v[182:183]
	v_lshl_add_u64 v[242:243], v[240:241], 0, s[80:81]
	v_lshl_add_u64 v[248:249], v[78:79], 0, v[182:183]
	v_lshl_add_u64 v[250:251], v[248:249], 0, s[80:81]
	v_lshl_add_u64 v[252:253], v[80:81], 0, v[182:183]
	v_lshl_add_u64 v[254:255], v[252:253], 0, s[80:81]
	global_load_dwordx4 v[82:85], v[240:241], off
	global_load_dwordx4 v[86:89], v[242:243], off
	global_load_dwordx4 v[90:93], v[248:249], off
	global_load_dwordx4 v[94:97], v[250:251], off
	global_load_dwordx4 v[98:101], v[252:253], off
	global_load_dwordx4 v[102:105], v[254:255], off
	global_load_dwordx4 v[106:109], v[240:241], off offset:64
	global_load_dwordx4 v[110:113], v[242:243], off offset:64
	global_load_dwordx4 v[132:135], v[248:249], off offset:64
	global_load_dwordx4 v[136:139], v[250:251], off offset:64
	global_load_dwordx4 v[140:143], v[252:253], off offset:64
	global_load_dwordx4 v[144:147], v[254:255], off offset:64
	global_load_dwordx4 v[148:151], v[240:241], off offset:128
	global_load_dwordx4 v[166:169], v[242:243], off offset:128
	global_load_dwordx4 v[170:173], v[248:249], off offset:128
	global_load_dwordx4 v[174:177], v[250:251], off offset:128
	global_load_dwordx4 v[198:201], v[252:253], off offset:128
	global_load_dwordx4 v[202:205], v[254:255], off offset:128
	global_load_dwordx4 v[216:219], v[240:241], off offset:192
	global_load_dwordx4 v[220:223], v[242:243], off offset:192
	global_load_dwordx4 v[224:227], v[248:249], off offset:192
	global_load_dwordx4 v[228:231], v[250:251], off offset:192
	global_load_dwordx4 v[232:235], v[252:253], off offset:192
	global_load_dwordx4 v[236:239], v[254:255], off offset:192
	s_waitcnt vmcnt(18)
	ds_write_b128 v194, v[82:85]
	ds_write_b128 v194, v[86:89] offset:1024
	ds_write_b128 v194, v[90:93] offset:2048
	ds_write_b128 v194, v[94:97] offset:3072
	ds_write_b128 v194, v[98:101] offset:4096
	ds_write_b128 v194, v[102:105] offset:5120
	ds_read_b128 v[82:85], v244
	ds_read_b128 v[86:89], v245
	ds_read_b128 v[90:93], v244 offset:2048
	ds_read_b128 v[94:97], v245 offset:2048
	ds_read_b128 v[98:101], v244 offset:4096
	ds_read_b128 v[102:105], v245 offset:4096
	s_waitcnt lgkmcnt(0)
	v_mfma_f32_32x32x16_bf16 v[2:17], v[82:85], v[90:93], 0
	v_mfma_f32_32x32x16_bf16 v[2:17], v[86:89], v[94:97], v[2:17]
	v_mfma_f32_32x32x16_bf16 v[18:33], v[82:85], v[98:101], 0
	v_mfma_f32_32x32x16_bf16 v[18:33], v[86:89], v[102:105], v[18:33]
	global_load_dwordx4 v[82:85], v[240:241], off offset:256
	global_load_dwordx4 v[86:89], v[242:243], off offset:256
	global_load_dwordx4 v[90:93], v[248:249], off offset:256
	global_load_dwordx4 v[94:97], v[250:251], off offset:256
	global_load_dwordx4 v[98:101], v[252:253], off offset:256
	global_load_dwordx4 v[102:105], v[254:255], off offset:256
	s_waitcnt vmcnt(18)
	ds_write_b128 v194, v[106:109]
	ds_write_b128 v194, v[110:113] offset:1024
	ds_write_b128 v194, v[132:135] offset:2048
	ds_write_b128 v194, v[136:139] offset:3072
	ds_write_b128 v194, v[140:143] offset:4096
	ds_write_b128 v194, v[144:147] offset:5120
	ds_read_b128 v[106:109], v244
	ds_read_b128 v[110:113], v245
	ds_read_b128 v[132:135], v244 offset:2048
	ds_read_b128 v[136:139], v245 offset:2048
	ds_read_b128 v[140:143], v244 offset:4096
	ds_read_b128 v[144:147], v245 offset:4096
	s_waitcnt lgkmcnt(0)
	v_mfma_f32_32x32x16_bf16 v[2:17], v[106:109], v[132:135], v[2:17]
	v_mfma_f32_32x32x16_bf16 v[2:17], v[110:113], v[136:139], v[2:17]
	v_mfma_f32_32x32x16_bf16 v[18:33], v[106:109], v[140:143], v[18:33]
	v_mfma_f32_32x32x16_bf16 v[18:33], v[110:113], v[144:147], v[18:33]
	global_load_dwordx4 v[106:109], v[240:241], off offset:320
	global_load_dwordx4 v[110:113], v[242:243], off offset:320
	global_load_dwordx4 v[132:135], v[248:249], off offset:320
	global_load_dwordx4 v[136:139], v[250:251], off offset:320
	global_load_dwordx4 v[140:143], v[252:253], off offset:320
	global_load_dwordx4 v[144:147], v[254:255], off offset:320
	s_waitcnt vmcnt(18)
	ds_write_b128 v194, v[148:151]
	ds_write_b128 v194, v[166:169] offset:1024
	ds_write_b128 v194, v[170:173] offset:2048
	ds_write_b128 v194, v[174:177] offset:3072
	ds_write_b128 v194, v[198:201] offset:4096
	ds_write_b128 v194, v[202:205] offset:5120
	ds_read_b128 v[148:151], v244
	ds_read_b128 v[166:169], v245
	ds_read_b128 v[170:173], v244 offset:2048
	ds_read_b128 v[174:177], v245 offset:2048
	ds_read_b128 v[198:201], v244 offset:4096
	ds_read_b128 v[202:205], v245 offset:4096
	s_waitcnt lgkmcnt(0)
	v_mfma_f32_32x32x16_bf16 v[2:17], v[148:151], v[170:173], v[2:17]
	v_mfma_f32_32x32x16_bf16 v[2:17], v[166:169], v[174:177], v[2:17]
	v_mfma_f32_32x32x16_bf16 v[18:33], v[148:151], v[198:201], v[18:33]
	v_mfma_f32_32x32x16_bf16 v[18:33], v[166:169], v[202:205], v[18:33]
	global_load_dwordx4 v[148:151], v[240:241], off offset:384
	global_load_dwordx4 v[166:169], v[242:243], off offset:384
	global_load_dwordx4 v[170:173], v[248:249], off offset:384
	global_load_dwordx4 v[174:177], v[250:251], off offset:384
	global_load_dwordx4 v[198:201], v[252:253], off offset:384
	global_load_dwordx4 v[202:205], v[254:255], off offset:384
	s_waitcnt vmcnt(18)
; template <class EpiS>
; DI void sample_gemm(LAS unsigned char* lds, const bf16_t* A, const bf16_t* Bt, int nN, int K, const EpiS& E) {
;     ...
; #pragma unroll 8
;         for (int ks = 0; ks < nk; ++ks) {
;             const bf16x8 a = *(const bf16x8*)(ap + ks * 16), b0 = *(const bf16x8*)(b0p + ks * 16), b1 = *(const bf16x8*)(b1p + ks * 16);
;             c0 = __builtin_amdgcn_mfma_f32_32x32x16_bf16(a, b0, c0, 0, 0, 0);
;             c1 = __builtin_amdgcn_mfma_f32_32x32x16_bf16(a, b1, c1, 0, 0, 0);
;         }
	ds_write_b128 v194, v[216:219]
	ds_write_b128 v194, v[220:223] offset:1024
	ds_write_b128 v194, v[224:227] offset:2048
	ds_write_b128 v194, v[228:231] offset:3072
	ds_write_b128 v194, v[232:235] offset:4096
	ds_write_b128 v194, v[236:239] offset:5120
	ds_read_b128 v[216:219], v244
	ds_read_b128 v[220:223], v245
	ds_read_b128 v[224:227], v244 offset:2048
	ds_read_b128 v[228:231], v245 offset:2048
	ds_read_b128 v[232:235], v244 offset:4096
	ds_read_b128 v[236:239], v245 offset:4096
	s_waitcnt lgkmcnt(0)
	v_mfma_f32_32x32x16_bf16 v[2:17], v[216:219], v[224:227], v[2:17]
	v_mfma_f32_32x32x16_bf16 v[2:17], v[220:223], v[228:231], v[2:17]
	v_mfma_f32_32x32x16_bf16 v[18:33], v[216:219], v[232:235], v[18:33]
	v_mfma_f32_32x32x16_bf16 v[18:33], v[220:223], v[236:239], v[18:33]
	global_load_dwordx4 v[216:219], v[240:241], off offset:448
	global_load_dwordx4 v[220:223], v[242:243], off offset:448
	global_load_dwordx4 v[224:227], v[248:249], off offset:448
	global_load_dwordx4 v[228:231], v[250:251], off offset:448
	global_load_dwordx4 v[232:235], v[252:253], off offset:448
	global_load_dwordx4 v[236:239], v[254:255], off offset:448
	s_waitcnt vmcnt(18)
	ds_write_b128 v194, v[82:85]
	ds_write_b128 v194, v[86:89] offset:1024
	ds_write_b128 v194, v[90:93] offset:2048
	ds_write_b128 v194, v[94:97] offset:3072
	ds_write_b128 v194, v[98:101] offset:4096
	ds_write_b128 v194, v[102:105] offset:5120
	ds_read_b128 v[82:85], v244
	ds_read_b128 v[86:89], v245
	ds_read_b128 v[90:93], v244 offset:2048
	ds_read_b128 v[94:97], v245 offset:2048
	ds_read_b128 v[98:101], v244 offset:4096
	ds_read_b128 v[102:105], v245 offset:4096
	s_waitcnt lgkmcnt(0)
	v_mfma_f32_32x32x16_bf16 v[2:17], v[82:85], v[90:93], v[2:17]
	v_mfma_f32_32x32x16_bf16 v[2:17], v[86:89], v[94:97], v[2:17]
	v_mfma_f32_32x32x16_bf16 v[18:33], v[82:85], v[98:101], v[18:33]
	v_mfma_f32_32x32x16_bf16 v[18:33], v[86:89], v[102:105], v[18:33]
	global_load_dwordx4 v[82:85], v[240:241], off offset:512
	global_load_dwordx4 v[86:89], v[242:243], off offset:512
	global_load_dwordx4 v[90:93], v[248:249], off offset:512
	global_load_dwordx4 v[94:97], v[250:251], off offset:512
	global_load_dwordx4 v[98:101], v[252:253], off offset:512
	global_load_dwordx4 v[102:105], v[254:255], off offset:512
	s_waitcnt vmcnt(18)
	ds_write_b128 v194, v[106:109]
	ds_write_b128 v194, v[110:113] offset:1024
	ds_write_b128 v194, v[132:135] offset:2048
	ds_write_b128 v194, v[136:139] offset:3072
	ds_write_b128 v194, v[140:143] offset:4096
	ds_write_b128 v194, v[144:147] offset:5120
	ds_read_b128 v[106:109], v244
	ds_read_b128 v[110:113], v245
	ds_read_b128 v[132:135], v244 offset:2048
	ds_read_b128 v[136:139], v245 offset:2048
	ds_read_b128 v[140:143], v244 offset:4096
	ds_read_b128 v[144:147], v245 offset:4096
	s_waitcnt lgkmcnt(0)
	v_mfma_f32_32x32x16_bf16 v[2:17], v[106:109], v[132:135], v[2:17]
	v_mfma_f32_32x32x16_bf16 v[2:17], v[110:113], v[136:139], v[2:17]
	v_mfma_f32_32x32x16_bf16 v[18:33], v[106:109], v[140:143], v[18:33]
	v_mfma_f32_32x32x16_bf16 v[18:33], v[110:113], v[144:147], v[18:33]
	global_load_dwordx4 v[106:109], v[240:241], off offset:576
	global_load_dwordx4 v[110:113], v[242:243], off offset:576
	global_load_dwordx4 v[132:135], v[248:249], off offset:576
	global_load_dwordx4 v[136:139], v[250:251], off offset:576
	global_load_dwordx4 v[140:143], v[252:253], off offset:576
	global_load_dwordx4 v[144:147], v[254:255], off offset:576
	s_waitcnt vmcnt(18)
	ds_write_b128 v194, v[148:151]
	ds_write_b128 v194, v[166:169] offset:1024
	ds_write_b128 v194, v[170:173] offset:2048
	ds_write_b128 v194, v[174:177] offset:3072
	ds_write_b128 v194, v[198:201] offset:4096
	ds_write_b128 v194, v[202:205] offset:5120
	ds_read_b128 v[148:151], v244
	ds_read_b128 v[166:169], v245
	ds_read_b128 v[170:173], v244 offset:2048
	ds_read_b128 v[174:177], v245 offset:2048
	ds_read_b128 v[198:201], v244 offset:4096
	ds_read_b128 v[202:205], v245 offset:4096
	s_waitcnt lgkmcnt(0)
	v_mfma_f32_32x32x16_bf16 v[2:17], v[148:151], v[170:173], v[2:17]
	v_mfma_f32_32x32x16_bf16 v[2:17], v[166:169], v[174:177], v[2:17]
	v_mfma_f32_32x32x16_bf16 v[18:33], v[148:151], v[198:201], v[18:33]
	v_mfma_f32_32x32x16_bf16 v[18:33], v[166:169], v[202:205], v[18:33]
	global_load_dwordx4 v[148:151], v[240:241], off offset:640
	global_load_dwordx4 v[166:169], v[242:243], off offset:640
	global_load_dwordx4 v[170:173], v[248:249], off offset:640
	global_load_dwordx4 v[174:177], v[250:251], off offset:640
	global_load_dwordx4 v[198:201], v[252:253], off offset:640
	global_load_dwordx4 v[202:205], v[254:255], off offset:640
	s_waitcnt vmcnt(18)
	ds_write_b128 v194, v[216:219]
	ds_write_b128 v194, v[220:223] offset:1024
	ds_write_b128 v194, v[224:227] offset:2048
	ds_write_b128 v194, v[228:231] offset:3072
	ds_write_b128 v194, v[232:235] offset:4096
	ds_write_b128 v194, v[236:239] offset:5120
	ds_read_b128 v[216:219], v244
	ds_read_b128 v[220:223], v245
	ds_read_b128 v[224:227], v244 offset:2048
	ds_read_b128 v[228:231], v245 offset:2048
	ds_read_b128 v[232:235], v244 offset:4096
	ds_read_b128 v[236:239], v245 offset:4096
	s_waitcnt lgkmcnt(0)
	v_mfma_f32_32x32x16_bf16 v[2:17], v[216:219], v[224:227], v[2:17]
	v_mfma_f32_32x32x16_bf16 v[2:17], v[220:223], v[228:231], v[2:17]
	v_mfma_f32_32x32x16_bf16 v[18:33], v[216:219], v[232:235], v[18:33]
	v_mfma_f32_32x32x16_bf16 v[18:33], v[220:223], v[236:239], v[18:33]
	s_waitcnt vmcnt(12)
; #define LAS __attribute__((address_space(3)))
; DI float bflo(unsigned u) { return __uint_as_float(u << 16); }
; DI float bfhi(unsigned u) { return __uint_as_float(u & 0xffff0000u); }
; DI float red16(float v) { v += __shfl_xor(v, 1); v += __shfl_xor(v, 2); v += __shfl_xor(v, 4); v += __shfl_xor(v, 8); return v; }
; DI u32x2 pk4(const f32x4 a) { return (u32x2){pk2(a[0], a[1]), pk2(a[2], a[3])}; }
;     DI void operator()(const f32x4 v, int row, int pn, int wc, int bj, int cl) const {
;     ...
;         else { const u32x2 w = *(const u32x2*)(XN + (size_t)row * D + col); x = (f32x4){bflo(w.x), bfhi(w.x), bflo(w.y), bfhi(w.y)}; }
;         x += v;
;         if (MODE == 2) *(f32x4*)(out + (size_t)row * D + col) = x;
;         else {
;             *(u32x2*)(XN + (size_t)row * D + col) = pk4(x);
;             const float ssq = red16((x[0] * x[0] + x[1] * x[1]) + (x[2] * x[2] + x[3] * x[3]));
;             if ((threadIdx.x & 15) == 0) atomicAdd(SS + row, ssq);
; template <class EpiS>
; DI void sample_gemm(LAS unsigned char* lds, const bf16_t* A, const bf16_t* Bt, int nN, int K, const EpiS& E) {
;     ...
;         __syncthreads();
;         LAS float* part = (LAS float*)(lds + w * 8192);
; #pragma unroll
;         for (int r = 0; r < 16; ++r) { const int row = (r & 3) + 8 * (r >> 2) + 4 * h; part[row * 64 + r32] = c0[r]; part[row * 64 + 32 + r32] = c1[r]; }
;         __syncthreads();
;         f32x4 v = (f32x4){0.f, 0.f, 0.f, 0.f};
; #pragma unroll
;         for (int ww = 0; ww < 8; ++ww) v += *(const LAS f32x4*)(lds + ww * 8192 + (tid >> 4) * 256 + (tid & 15) * 16);
;         E(v, MP + rb * 32 + (tid >> 4), pn, wc, (tid >> 3) & 1, 4 * (tid & 7));
	ds_write_b128 v194, v[82:85]
	ds_write_b128 v194, v[86:89] offset:1024
	ds_write_b128 v194, v[90:93] offset:2048
	ds_write_b128 v194, v[94:97] offset:3072
	ds_write_b128 v194, v[98:101] offset:4096
	ds_write_b128 v194, v[102:105] offset:5120
	ds_read_b128 v[82:85], v244
	ds_read_b128 v[86:89], v245
	ds_read_b128 v[90:93], v244 offset:2048
	ds_read_b128 v[94:97], v245 offset:2048
	ds_read_b128 v[98:101], v244 offset:4096
	ds_read_b128 v[102:105], v245 offset:4096
	s_waitcnt lgkmcnt(0)
	v_mfma_f32_32x32x16_bf16 v[2:17], v[82:85], v[90:93], v[2:17]
	v_mfma_f32_32x32x16_bf16 v[2:17], v[86:89], v[94:97], v[2:17]
	v_mfma_f32_32x32x16_bf16 v[18:33], v[82:85], v[98:101], v[18:33]
	v_mfma_f32_32x32x16_bf16 v[18:33], v[86:89], v[102:105], v[18:33]
	s_waitcnt vmcnt(6)
	ds_write_b128 v194, v[106:109]
	ds_write_b128 v194, v[110:113] offset:1024
	ds_write_b128 v194, v[132:135] offset:2048
	ds_write_b128 v194, v[136:139] offset:3072
	ds_write_b128 v194, v[140:143] offset:4096
	ds_write_b128 v194, v[144:147] offset:5120
	ds_read_b128 v[106:109], v244
	ds_read_b128 v[110:113], v245
	ds_read_b128 v[132:135], v244 offset:2048
	ds_read_b128 v[136:139], v245 offset:2048
	ds_read_b128 v[140:143], v244 offset:4096
	ds_read_b128 v[144:147], v245 offset:4096
	s_waitcnt lgkmcnt(0)
	v_mfma_f32_32x32x16_bf16 v[2:17], v[106:109], v[132:135], v[2:17]
	v_mfma_f32_32x32x16_bf16 v[2:17], v[110:113], v[136:139], v[2:17]
	v_mfma_f32_32x32x16_bf16 v[18:33], v[106:109], v[140:143], v[18:33]
	v_mfma_f32_32x32x16_bf16 v[18:33], v[110:113], v[144:147], v[18:33]
	s_waitcnt vmcnt(0)
	ds_write_b128 v194, v[148:151]
	ds_write_b128 v194, v[166:169] offset:1024
	ds_write_b128 v194, v[170:173] offset:2048
	ds_write_b128 v194, v[174:177] offset:3072
	ds_write_b128 v194, v[198:201] offset:4096
	ds_write_b128 v194, v[202:205] offset:5120
	ds_read_b128 v[148:151], v244
	ds_read_b128 v[166:169], v245
	ds_read_b128 v[170:173], v244 offset:2048
	ds_read_b128 v[174:177], v245 offset:2048
	ds_read_b128 v[198:201], v244 offset:4096
	ds_read_b128 v[202:205], v245 offset:4096
	s_waitcnt lgkmcnt(0)
	v_mfma_f32_32x32x16_bf16 v[2:17], v[148:151], v[170:173], v[2:17]
	v_mfma_f32_32x32x16_bf16 v[2:17], v[166:169], v[174:177], v[2:17]
	v_mfma_f32_32x32x16_bf16 v[18:33], v[148:151], v[198:201], v[18:33]
	v_mfma_f32_32x32x16_bf16 v[18:33], v[166:169], v[202:205], v[18:33]
	s_barrier
	s_nop 11
	ds_write2_b32 v41, v2, v18 offset1:32
	ds_write2_b32 v41, v3, v19 offset0:64 offset1:96
	ds_write2_b32 v41, v4, v20 offset0:128 offset1:160
	ds_write2_b32 v41, v5, v21 offset0:192 offset1:224
	ds_write2_b32 v48, v6, v22 offset1:32
	ds_write2_b32 v48, v7, v23 offset0:64 offset1:96
	ds_write2_b32 v48, v8, v24 offset0:128 offset1:160
	ds_write2_b32 v48, v9, v25 offset0:192 offset1:224
	ds_write2_b32 v49, v10, v26 offset1:32
	ds_write2_b32 v49, v11, v27 offset0:64 offset1:96
	ds_write2_b32 v49, v12, v28 offset0:128 offset1:160
	ds_write2_b32 v49, v13, v29 offset0:192 offset1:224
	ds_write2_b32 v50, v14, v30 offset1:32
	ds_write2_b32 v50, v15, v31 offset0:64 offset1:96
	ds_write2_b32 v50, v16, v32 offset0:128 offset1:160
	ds_write2_b32 v50, v17, v33 offset0:192 offset1:224
	s_waitcnt lgkmcnt(0)
	s_barrier
	ds_read_b128 v[4:7], v47
	ds_read_b128 v[8:11], v47 offset:8192
	ds_read_b128 v[12:15], v47 offset:16384
	s_waitcnt lgkmcnt(2)
	v_pk_add_f32 v[6:7], v[6:7], 0 op_sel_hi:[1,0]
	v_pk_add_f32 v[16:17], v[4:5], 0 op_sel_hi:[1,0]
	s_waitcnt lgkmcnt(1)
	v_pk_add_f32 v[10:11], v[6:7], v[10:11]
	ds_read_b128 v[4:7], v47 offset:24576
	v_pk_add_f32 v[16:17], v[16:17], v[8:9]
	s_waitcnt lgkmcnt(1)
	v_pk_add_f32 v[14:15], v[10:11], v[14:15]
	ds_read_b128 v[8:11], v47 offset:32768
	v_pk_add_f32 v[12:13], v[16:17], v[12:13]
	s_waitcnt lgkmcnt(1)
	v_pk_add_f32 v[14:15], v[14:15], v[6:7]
	v_pk_add_f32 v[16:17], v[12:13], v[4:5]
	ds_read_b128 v[4:7], v47 offset:40960
	s_waitcnt lgkmcnt(1)
	v_pk_add_f32 v[22:23], v[14:15], v[10:11]
	ds_read_b128 v[10:13], v47 offset:49152
	v_pk_add_f32 v[8:9], v[16:17], v[8:9]
	ds_read_b128 v[14:17], v47 offset:57344
	s_waitcnt lgkmcnt(2)
	v_pk_add_f32 v[6:7], v[22:23], v[6:7]
	v_pk_add_f32 v[4:5], v[8:9], v[4:5]
	s_waitcnt lgkmcnt(1)
	v_pk_add_f32 v[6:7], v[6:7], v[12:13]
	v_pk_add_f32 v[4:5], v[4:5], v[10:11]
	s_waitcnt lgkmcnt(0)
	v_pk_add_f32 v[6:7], v[6:7], v[16:17]
	v_pk_add_f32 v[4:5], v[4:5], v[14:15]
	s_waitcnt vmcnt(0)
	v_lshlrev_b32_e32 v8, 16, v208
	v_and_b32_e32 v9, 0xffff0000, v208
	v_lshlrev_b32_e32 v10, 16, v209
	v_and_b32_e32 v11, 0xffff0000, v209
	v_pk_add_f32 v[6:7], v[6:7], v[10:11]
	v_pk_add_f32 v[8:9], v[4:5], v[8:9]
	v_mul_f32_e32 v4, v7, v7
	v_mul_f32_e32 v3, v9, v9
	v_fmac_f32_e32 v3, v8, v8
	v_fmac_f32_e32 v4, v6, v6
	v_add_f32_e32 v3, v3, v4
	ds_bpermute_b32 v4, v43, v3
	v_cvt_pk_bf16_f32 v8, v8, v9
	v_cvt_pk_bf16_f32 v9, v6, v7
	global_store_dwordx2 v[206:207], v[8:9], off
	s_waitcnt lgkmcnt(0)
	v_add_f32_e32 v3, v3, v4
	ds_bpermute_b32 v4, v44, v3
	s_waitcnt lgkmcnt(0)
	v_add_f32_e32 v3, v3, v4
	ds_bpermute_b32 v4, v45, v3
	s_waitcnt lgkmcnt(0)
	v_add_f32_e32 v3, v3, v4
	ds_bpermute_b32 v4, v46, v3
	s_and_saveexec_b64 s[0:1], vcc
	s_cbranch_execz .LBB0_721
	s_waitcnt lgkmcnt(0)
	v_add_f32_e32 v3, v3, v4
	v_lshlrev_b32_e32 v2, 2, v210
	global_atomic_add_f32 v2, v3, s[10:11]
	s_branch .LBB0_721

; DI float row_rstd(const float* SS, int row) { return rsqrtf(SS[row] * (1.0f / 1024.0f) + 1e-6f); }
;     DI void operator()(const f32x4 v, int row, int pn, int wc, int bj, int cl) const {
;     ...
;         const float rs = row_rstd(SS, row);
; template <class EpiS>
; DI void sample_gemm(LAS unsigned char* lds, const bf16_t* A, const bf16_t* Bt, int nN, int K, const EpiS& E) {
;     ...
;     for (int un = (int)blockIdx.x; un < nunits; un += (int)gridDim.x) {
;         const int rb = un & 3, wc = (un >> 2) & 3, pn = un >> 4;
;         const bf16_t* ap = A + (size_t)(MP + rb * 32 + r32) * K + w * kw + h * 8;
;         const bf16_t* b0p = Bt + (size_t)(pn * 256 + wc * 32 + r32) * K + w * kw + h * 8;
;         const bf16_t* b1p = b0p + (size_t)128 * K;
;         f32x16 c0, c1;
; #pragma unroll
;         for (int r = 0; r < 16; ++r) { c0[r] = 0.f; c1[r] = 0.f; }
; #pragma unroll 8
;         for (int ks = 0; ks < nk; ++ks) {
;             const bf16x8 a = *(const bf16x8*)(ap + ks * 16), b0 = *(const bf16x8*)(b0p + ks * 16), b1 = *(const bf16x8*)(b1p + ks * 16);
;             c0 = __builtin_amdgcn_mfma_f32_32x32x16_bf16(a, b0, c0, 0, 0, 0);
;             c1 = __builtin_amdgcn_mfma_f32_32x32x16_bf16(a, b1, c1, 0, 0, 0);
;         }
.LBB0_935:
	s_and_b32 s6, s10, 0x60
	s_bitset1_b32 s6, 15
	s_bfe_u32 s4, s14, 0x20002
	s_ashr_i32 s15, s14, 4
	v_or_b32_e32 v3, s6, v37
	s_lshl_b32 s7, s15, 8
	s_lshl_b32 s33, s4, 5
	v_lshlrev_b32_e32 v34, 11, v3
	s_or_b32 s7, s33, s7
	v_lshl_add_u64 v[76:77], v[38:39], 0, v[34:35]
	v_or_b32_e32 v2, s7, v37
	v_ashrrev_i32_e32 v3, 31, v2
	v_lshlrev_b64 v[2:3], 11, v[2:3]
	v_lshl_add_u64 v[78:79], v[40:41], 0, v[2:3]
	v_add_co_u32_e32 v80, vcc, s12, v78
	s_ashr_i32 s18, s14, 5
	s_nop 0
	v_addc_co_u32_e32 v81, vcc, 0, v79, vcc
	s_and_b32 s19, s15, 1
	s_mul_hi_i32 s7, s18, 0x2040000
	s_mov_b64 s[8:9], -1
	s_waitcnt vmcnt(6) lgkmcnt(0)
	s_waitcnt lgkmcnt(0)
	v_add_u32_e32 v52, s6, v157
	v_lshlrev_b32_e32 v34, 2, v52
	s_mul_i32 s6, s18, 0x2040000
	s_add_u32 s6, s24, s6
	s_addc_u32 s7, s25, s7
	s_cmp_gt_i32 s18, 1
	global_load_dword v34, v34, s[16:17]
	v_lshl_add_u64 v[158:159], v[76:77], 0, v[182:183]
	v_lshl_add_u64 v[160:161], v[78:79], 0, v[182:183]
	v_lshl_add_u64 v[180:181], v[80:81], 0, v[182:183]
	global_load_dwordx4 v[82:85], v[158:159], off
	v_lshl_add_u64 v[158:159], v[158:159], 0, s[80:81]
	global_load_dwordx4 v[86:89], v[158:159], off
	v_lshl_add_u64 v[158:159], v[158:159], 0, s[80:81]
	global_load_dwordx4 v[90:93], v[158:159], off
	v_lshl_add_u64 v[158:159], v[158:159], 0, s[80:81]
	global_load_dwordx4 v[94:97], v[158:159], off
	v_lshl_add_u64 v[158:159], v[158:159], 0, s[82:83]
	global_load_dwordx4 v[98:101], v[160:161], off
	v_lshl_add_u64 v[160:161], v[160:161], 0, s[80:81]
	global_load_dwordx4 v[102:105], v[160:161], off
	v_lshl_add_u64 v[160:161], v[160:161], 0, s[80:81]
	global_load_dwordx4 v[106:109], v[160:161], off
	v_lshl_add_u64 v[160:161], v[160:161], 0, s[80:81]
	global_load_dwordx4 v[110:113], v[160:161], off
	v_lshl_add_u64 v[160:161], v[160:161], 0, s[82:83]
	global_load_dwordx4 v[132:135], v[180:181], off
	v_lshl_add_u64 v[180:181], v[180:181], 0, s[80:81]
	global_load_dwordx4 v[136:139], v[180:181], off
	v_lshl_add_u64 v[180:181], v[180:181], 0, s[80:81]
	global_load_dwordx4 v[140:143], v[180:181], off
	v_lshl_add_u64 v[180:181], v[180:181], 0, s[80:81]
	global_load_dwordx4 v[144:147], v[180:181], off
	v_lshl_add_u64 v[180:181], v[180:181], 0, s[82:83]
	global_load_dwordx4 v[148:151], v[158:159], off offset:128
	v_lshl_add_u64 v[158:159], v[158:159], 0, s[80:81]
	global_load_dwordx4 v[166:169], v[158:159], off offset:128
	v_lshl_add_u64 v[158:159], v[158:159], 0, s[80:81]
	global_load_dwordx4 v[170:173], v[158:159], off offset:128
	v_lshl_add_u64 v[158:159], v[158:159], 0, s[80:81]
	global_load_dwordx4 v[174:177], v[158:159], off offset:128
	global_load_dwordx4 v[198:201], v[160:161], off offset:128
	v_lshl_add_u64 v[160:161], v[160:161], 0, s[80:81]
	global_load_dwordx4 v[202:205], v[160:161], off offset:128
	v_lshl_add_u64 v[160:161], v[160:161], 0, s[80:81]
	global_load_dwordx4 v[216:219], v[160:161], off offset:128
	v_lshl_add_u64 v[160:161], v[160:161], 0, s[80:81]
	global_load_dwordx4 v[220:223], v[160:161], off offset:128
	global_load_dwordx4 v[224:227], v[180:181], off offset:128
	v_lshl_add_u64 v[180:181], v[180:181], 0, s[80:81]
	global_load_dwordx4 v[228:231], v[180:181], off offset:128
	v_lshl_add_u64 v[180:181], v[180:181], 0, s[80:81]
	global_load_dwordx4 v[232:235], v[180:181], off offset:128
	v_lshl_add_u64 v[180:181], v[180:181], 0, s[80:81]
	global_load_dwordx4 v[236:239], v[180:181], off offset:128
	s_waitcnt vmcnt(16)
	ds_write_b128 v194, v[82:85]
	ds_write_b128 v195, v[86:89] offset:1024
	ds_write_b128 v194, v[90:93] offset:2048
	ds_write_b128 v195, v[94:97] offset:3072
	ds_write_b128 v194, v[98:101] offset:4096
	ds_write_b128 v195, v[102:105] offset:5120
	ds_write_b128 v194, v[106:109] offset:6144
	ds_write_b128 v195, v[110:113] offset:7168
	ds_read_b128 v[82:85], v244
	ds_read_b128 v[86:89], v245
	ds_read_b128 v[90:93], v246
	ds_read_b128 v[94:97], v193
	ds_read_b128 v[98:101], v244 offset:4096
	ds_read_b128 v[102:105], v245 offset:4096
	ds_read_b128 v[106:109], v246 offset:4096
	ds_read_b128 v[110:113], v193 offset:4096
	s_waitcnt lgkmcnt(0)
	v_mfma_f32_32x32x16_bf16 v[2:17], v[82:85], v[98:101], 0
	v_mfma_f32_32x32x16_bf16 v[2:17], v[86:89], v[102:105], v[2:17]
	v_mfma_f32_32x32x16_bf16 v[2:17], v[90:93], v[106:109], v[2:17]
	v_mfma_f32_32x32x16_bf16 v[2:17], v[94:97], v[110:113], v[2:17]
	s_waitcnt vmcnt(12)
	ds_write_b128 v194, v[132:135] offset:4096
	ds_write_b128 v195, v[136:139] offset:5120
	ds_write_b128 v194, v[140:143] offset:6144
	ds_write_b128 v195, v[144:147] offset:7168
	ds_read_b128 v[132:135], v244 offset:4096
	ds_read_b128 v[136:139], v245 offset:4096
	ds_read_b128 v[140:143], v246 offset:4096
	ds_read_b128 v[144:147], v193 offset:4096
	s_waitcnt lgkmcnt(0)
	v_mfma_f32_32x32x16_bf16 v[18:33], v[82:85], v[132:135], 0
	v_mfma_f32_32x32x16_bf16 v[18:33], v[86:89], v[136:139], v[18:33]
	v_mfma_f32_32x32x16_bf16 v[18:33], v[90:93], v[140:143], v[18:33]
	v_mfma_f32_32x32x16_bf16 v[18:33], v[94:97], v[144:147], v[18:33]
	s_waitcnt vmcnt(4)
	ds_write_b128 v194, v[148:151]
	ds_write_b128 v195, v[166:169] offset:1024
	ds_write_b128 v194, v[170:173] offset:2048
	ds_write_b128 v195, v[174:177] offset:3072
	ds_write_b128 v194, v[198:201] offset:4096
	ds_write_b128 v195, v[202:205] offset:5120
	ds_write_b128 v194, v[216:219] offset:6144
	ds_write_b128 v195, v[220:223] offset:7168
	ds_read_b128 v[148:151], v244
	ds_read_b128 v[166:169], v245
	ds_read_b128 v[170:173], v246
	ds_read_b128 v[174:177], v193
	ds_read_b128 v[198:201], v244 offset:4096
	ds_read_b128 v[202:205], v245 offset:4096
	ds_read_b128 v[216:219], v246 offset:4096
	ds_read_b128 v[220:223], v193 offset:4096
	s_waitcnt lgkmcnt(0)
	v_mfma_f32_32x32x16_bf16 v[2:17], v[148:151], v[198:201], v[2:17]
	v_mfma_f32_32x32x16_bf16 v[2:17], v[166:169], v[202:205], v[2:17]
	v_mfma_f32_32x32x16_bf16 v[2:17], v[170:173], v[216:219], v[2:17]
	v_mfma_f32_32x32x16_bf16 v[2:17], v[174:177], v[220:223], v[2:17]
	s_waitcnt vmcnt(0)
	ds_write_b128 v194, v[224:227] offset:4096
	ds_write_b128 v195, v[228:231] offset:5120
	ds_write_b128 v194, v[232:235] offset:6144
	ds_write_b128 v195, v[236:239] offset:7168
	ds_read_b128 v[224:227], v244 offset:4096
	ds_read_b128 v[228:231], v245 offset:4096
	ds_read_b128 v[232:235], v246 offset:4096
	ds_read_b128 v[236:239], v193 offset:4096
	s_waitcnt lgkmcnt(0)
	v_mfma_f32_32x32x16_bf16 v[18:33], v[148:151], v[224:227], v[18:33]
	v_mfma_f32_32x32x16_bf16 v[18:33], v[166:169], v[228:231], v[18:33]
	v_mfma_f32_32x32x16_bf16 v[18:33], v[170:173], v[232:235], v[18:33]
	v_mfma_f32_32x32x16_bf16 v[18:33], v[174:177], v[236:239], v[18:33]
	s_barrier
; #define LAS __attribute__((address_space(3)))
; DI float row_rstd(const float* SS, int row) { return rsqrtf(SS[row] * (1.0f / 1024.0f) + 1e-6f); }
; DI float red16(float v) { v += __shfl_xor(v, 1); v += __shfl_xor(v, 2); v += __shfl_xor(v, 4); v += __shfl_xor(v, 8); return v; }
; DI u32x2 pk4(const f32x4 a) { return (u32x2){pk2(a[0], a[1]), pk2(a[2], a[3])}; }
;     DI void operator()(const f32x4 v, int row, int pn, int wc, int bj, int cl) const {
;     ...
;         const float rs = row_rstd(SS, row);
;         const f32x4 x = v * rs;
;         if (typ < 2) {
;             const int head = ph * 4 + wc, dd = 32 * bj + cl;
;             const float ssq = red16((x[0] * x[0] + x[1] * x[1]) + (x[2] * x[2] + x[3] * x[3]));
;             const float r = rsqrtf(ssq * (1.0f / 64.0f) + 1e-6f);
;             const f32x4 gv = *(const f32x4*)((typ == 0 ? qg : kg) + dd);
;             const f32x4 o = x * r * gv;
;             *(u32x2*)(O + (size_t)row * MW + head * 64 + dd) = pk4(o * (typ == 0 ? QSCALE : 1.0f));
;             if (typ == 1) *(f32x4*)(out + O_KS + (size_t)(row - MP) * 512 + head * 64 + dd) = o;
;         } else {
;             const int col = ph * 256 + bj * 128 + wc * 32 + cl;
;             *(u32x2*)(O + (size_t)row * MW + col) = pk4(x);
;             if (typ == 2) *(f32x4*)(out + O_VS + (size_t)(row - MP) * 512 + col) = x;
;             if (typ == 4) {
;                 const float s1 = red16((x[0] + x[1]) + (x[2] + x[3])), s2 = red16((x[0] * x[0] + x[1] * x[1]) + (x[2] * x[2] + x[3] * x[3]));
;                 if ((threadIdx.x & 15) == 0) *(f32x2*)(SVST + ((size_t)row * 8 + ph * 4 + wc) * 2) = (f32x2){s1, s2};
; template <class EpiS>
; DI void sample_gemm(LAS unsigned char* lds, const bf16_t* A, const bf16_t* Bt, int nN, int K, const EpiS& E) {
;     ...
;         __syncthreads();
;         LAS float* part = (LAS float*)(lds + w * 8192);
; #pragma unroll
;         for (int r = 0; r < 16; ++r) { const int row = (r & 3) + 8 * (r >> 2) + 4 * h; part[row * 64 + r32] = c0[r]; part[row * 64 + 32 + r32] = c1[r]; }
;         __syncthreads();
;         f32x4 v = (f32x4){0.f, 0.f, 0.f, 0.f};
; #pragma unroll
;         for (int ww = 0; ww < 8; ++ww) v += *(const LAS f32x4*)(lds + ww * 8192 + (tid >> 4) * 256 + (tid & 15) * 16);
;         E(v, MP + rb * 32 + (tid >> 4), pn, wc, (tid >> 3) & 1, 4 * (tid & 7));
	s_nop 11
	ds_write2_b32 v44, v2, v18 offset1:32
	ds_write2_b32 v44, v3, v19 offset0:64 offset1:96
	ds_write2_b32 v44, v4, v20 offset0:128 offset1:160
	ds_write2_b32 v44, v5, v21 offset0:192 offset1:224
	ds_write2_b32 v47, v6, v22 offset1:32
	ds_write2_b32 v47, v7, v23 offset0:64 offset1:96
	ds_write2_b32 v47, v8, v24 offset0:128 offset1:160
	ds_write2_b32 v47, v9, v25 offset0:192 offset1:224
	ds_write2_b32 v48, v10, v26 offset1:32
	ds_write2_b32 v48, v11, v27 offset0:64 offset1:96
	ds_write2_b32 v48, v12, v28 offset0:128 offset1:160
	ds_write2_b32 v48, v13, v29 offset0:192 offset1:224
	ds_write2_b32 v49, v14, v30 offset1:32
	ds_write2_b32 v49, v15, v31 offset0:64 offset1:96
	ds_write2_b32 v49, v16, v32 offset0:128 offset1:160
	ds_write2_b32 v49, v17, v33 offset0:192 offset1:224
	s_waitcnt lgkmcnt(0)
	s_barrier
	ds_read_b128 v[2:5], v45
	ds_read_b128 v[6:9], v45 offset:8192
	ds_read_b128 v[10:13], v45 offset:16384
	ds_read_b128 v[14:17], v45 offset:24576
	ds_read_b128 v[18:21], v45 offset:32768
	ds_read_b128 v[22:25], v45 offset:40960
	ds_read_b128 v[26:29], v45 offset:49152
	ds_read_b128 v[30:33], v45 offset:57344
	s_waitcnt lgkmcnt(7)
	v_pk_add_f32 v[2:3], v[2:3], 0 op_sel_hi:[1,0]
	v_pk_add_f32 v[4:5], v[4:5], 0 op_sel_hi:[1,0]
	s_waitcnt lgkmcnt(6)
	v_pk_add_f32 v[2:3], v[2:3], v[6:7]
	v_pk_add_f32 v[4:5], v[4:5], v[8:9]
	s_waitcnt lgkmcnt(5)
	v_pk_add_f32 v[2:3], v[2:3], v[10:11]
	v_pk_add_f32 v[4:5], v[4:5], v[12:13]
	s_waitcnt lgkmcnt(4)
	v_pk_add_f32 v[2:3], v[2:3], v[14:15]
	v_pk_add_f32 v[4:5], v[4:5], v[16:17]
	s_waitcnt lgkmcnt(3)
	v_pk_add_f32 v[2:3], v[2:3], v[18:19]
	v_pk_add_f32 v[4:5], v[4:5], v[20:21]
	s_waitcnt lgkmcnt(2)
	v_pk_add_f32 v[2:3], v[2:3], v[22:23]
	v_pk_add_f32 v[4:5], v[4:5], v[24:25]
	s_waitcnt lgkmcnt(1)
	v_pk_add_f32 v[2:3], v[2:3], v[26:27]
	v_pk_add_f32 v[4:5], v[4:5], v[28:29]
	s_waitcnt lgkmcnt(0)
	v_pk_add_f32 v[2:3], v[2:3], v[30:31]
	v_pk_add_f32 v[4:5], v[4:5], v[32:33]
	s_waitcnt vmcnt(0)
	v_fmamk_f32 v6, v34, 0x3a800000, v46
	v_mul_f32_e32 v7, 0x4b800000, v6
	v_cmp_gt_f32_e32 vcc, s13, v6
	v_lshlrev_b32_e32 v34, 10, v52
	s_nop 0
	v_cndmask_b32_e32 v6, v6, v7, vcc
	v_rsq_f32_e32 v6, v6
	s_nop 0
	v_mul_f32_e32 v7, 0x45800000, v6
	v_cndmask_b32_e32 v6, v6, v7, vcc
	v_pk_mul_f32 v[2:3], v[2:3], v[6:7] op_sel_hi:[1,0]
	v_pk_mul_f32 v[4:5], v[4:5], v[6:7] op_sel_hi:[1,0]
	s_cbranch_scc0 .LBB0_944
	v_lshl_or_b32 v6, s19, 8, v43
	v_or3_b32 v6, v6, s33, v42
	v_lshl_add_u64 v[10:11], s[6:7], 0, v[34:35]
	v_lshlrev_b32_e32 v12, 1, v6
	v_mov_b32_e32 v13, v35
	v_cvt_pk_bf16_f32 v8, v2, v3
	v_cvt_pk_bf16_f32 v9, v4, v5
	v_lshl_add_u64 v[10:11], v[10:11], 0, v[12:13]
	s_cmp_gt_i32 s18, 3
	global_store_dwordx2 v[10:11], v[8:9], off
	s_cbranch_scc0 .LBB0_940
	v_and_b32_e32 v8, 64, v50
	v_xor_b32_e32 v7, 1, v50
	v_add_u32_e32 v16, 64, v8
	v_cmp_lt_i32_e32 vcc, v7, v16
	v_mul_f32_e32 v9, v2, v2
	v_mul_f32_e32 v11, v3, v3
	v_mul_f32_e32 v13, v4, v4
	v_mul_f32_e32 v15, v5, v5
	v_mov_b32_e32 v8, v2
	v_mov_b32_e32 v10, v3
	v_mov_b32_e32 v12, v4
	v_mov_b32_e32 v14, v5
	v_cndmask_b32_e32 v7, v50, v7, vcc
	v_pk_add_f32 v[8:9], v[8:9], v[10:11]
	v_pk_add_f32 v[10:11], v[12:13], v[14:15]
	v_lshlrev_b32_e32 v7, 2, v7
	v_pk_add_f32 v[8:9], v[8:9], v[10:11]
	ds_bpermute_b32 v10, v7, v8
	ds_bpermute_b32 v11, v7, v9
	v_xor_b32_e32 v7, 2, v50
	v_cmp_lt_i32_e32 vcc, v7, v16
	s_waitcnt lgkmcnt(0)
	v_pk_add_f32 v[8:9], v[8:9], v[10:11]
	v_cndmask_b32_e32 v7, v50, v7, vcc
	v_lshlrev_b32_e32 v7, 2, v7
	ds_bpermute_b32 v10, v7, v8
	ds_bpermute_b32 v11, v7, v9
	v_xor_b32_e32 v7, 4, v50
	v_cmp_lt_i32_e32 vcc, v7, v16
	s_waitcnt lgkmcnt(0)
	v_pk_add_f32 v[8:9], v[8:9], v[10:11]
	v_cndmask_b32_e32 v7, v50, v7, vcc
	v_lshlrev_b32_e32 v7, 2, v7
	ds_bpermute_b32 v10, v7, v8
	ds_bpermute_b32 v11, v7, v9
	v_xor_b32_e32 v7, 8, v50
	v_cmp_lt_i32_e32 vcc, v7, v16
	s_waitcnt lgkmcnt(0)
	v_pk_add_f32 v[8:9], v[8:9], v[10:11]
	v_cndmask_b32_e32 v7, v50, v7, vcc
	v_lshlrev_b32_e32 v7, 2, v7
	ds_bpermute_b32 v10, v7, v8
	ds_bpermute_b32 v11, v7, v9
	s_and_saveexec_b64 s[8:9], s[0:1]
	s_cbranch_execz .LBB0_939
	s_lshl_b32 s33, s19, 2
	v_lshl_or_b32 v7, v52, 3, s33
	v_or_b32_e32 v7, s4, v7
	v_readlane_b32 s50, v247, 7
	v_lshlrev_b32_e32 v7, 3, v7
	s_waitcnt lgkmcnt(0)
	v_pk_add_f32 v[8:9], v[8:9], v[10:11]
	v_readlane_b32 s51, v247, 8
	s_nop 4
	global_store_dwordx2 v7, v[8:9], s[50:51]

; DI float bflo(unsigned u) { return __uint_as_float(u << 16); }
; DI float bfhi(unsigned u) { return __uint_as_float(u & 0xffff0000u); }
;     DI void operator()(const f32x4 v, int row, int pn, int wc, int bj, int cl) const {
;     ...
;         else { const u32x2 w = *(const u32x2*)(XN + (size_t)row * D + col); x = (f32x4){bflo(w.x), bfhi(w.x), bflo(w.y), bfhi(w.y)}; }
; template <class EpiS>
; DI void sample_gemm(LAS unsigned char* lds, const bf16_t* A, const bf16_t* Bt, int nN, int K, const EpiS& E) {
;     ...
;     for (int un = (int)blockIdx.x; un < nunits; un += (int)gridDim.x) {
;         const int rb = un & 3, wc = (un >> 2) & 3, pn = un >> 4;
;         const bf16_t* ap = A + (size_t)(MP + rb * 32 + r32) * K + w * kw + h * 8;
;         const bf16_t* b0p = Bt + (size_t)(pn * 256 + wc * 32 + r32) * K + w * kw + h * 8;
;         const bf16_t* b1p = b0p + (size_t)128 * K;
;         f32x16 c0, c1;
; #pragma unroll
;         for (int r = 0; r < 16; ++r) { c0[r] = 0.f; c1[r] = 0.f; }
; #pragma unroll 8
;         for (int ks = 0; ks < nk; ++ks) {
;             const bf16x8 a = *(const bf16x8*)(ap + ks * 16), b0 = *(const bf16x8*)(b0p + ks * 16), b1 = *(const bf16x8*)(b1p + ks * 16);
;             c0 = __builtin_amdgcn_mfma_f32_32x32x16_bf16(a, b0, c0, 0, 0, 0);
;             c1 = __builtin_amdgcn_mfma_f32_32x32x16_bf16(a, b1, c1, 0, 0, 0);
;         }
.LBB0_1365:
	s_and_b32 s0, s12, 0x60
	s_or_b32 s16, s0, 0x8000
	s_waitcnt lgkmcnt(0)
	v_or_b32_e32 v3, s16, v40
	s_and_b32 s0, s10, 0xffffff00
	s_and_b32 s1, s4, 0x60
	v_lshlrev_b32_e32 v34, 11, v3
	s_or_b32 s17, s0, s1
	v_lshl_add_u64 v[76:77], v[36:37], 0, v[34:35]
	v_or_b32_e32 v2, s17, v40
	v_ashrrev_i32_e32 v3, 31, v2
	v_lshlrev_b64 v[2:3], 11, v[2:3]
	v_lshl_add_u64 v[78:79], v[38:39], 0, v[2:3]
	v_add_co_u32_e64 v80, s[0:1], s14, v78
	v_add_u32_e32 v51, s16, v188
	s_nop 0
	v_addc_co_u32_e64 v81, s[0:1], 0, v79, s[0:1]
	v_lshlrev_b32_e32 v34, 11, v51
	v_or_b32_e32 v60, s17, v42
	v_ashrrev_i32_e32 v61, 31, v60
	v_lshl_add_u64 v[56:57], s[34:35], 0, v[34:35]
	v_lshl_add_u64 v[56:57], v[60:61], 1, v[56:57]
	global_load_dwordx2 v[240:241], v[56:57], off
	v_lshl_add_u64 v[158:159], v[76:77], 0, v[182:183]
	v_lshl_add_u64 v[160:161], v[78:79], 0, v[182:183]
	v_lshl_add_u64 v[180:181], v[80:81], 0, v[182:183]
	global_load_dwordx4 v[82:85], v[158:159], off
	v_lshl_add_u64 v[158:159], v[158:159], 0, s[80:81]
	global_load_dwordx4 v[86:89], v[158:159], off
	v_lshl_add_u64 v[158:159], v[158:159], 0, s[80:81]
	global_load_dwordx4 v[90:93], v[158:159], off
	v_lshl_add_u64 v[158:159], v[158:159], 0, s[80:81]
	global_load_dwordx4 v[94:97], v[158:159], off
	v_lshl_add_u64 v[158:159], v[158:159], 0, s[82:83]
	global_load_dwordx4 v[98:101], v[160:161], off
	v_lshl_add_u64 v[160:161], v[160:161], 0, s[80:81]
	global_load_dwordx4 v[102:105], v[160:161], off
	v_lshl_add_u64 v[160:161], v[160:161], 0, s[80:81]
	global_load_dwordx4 v[106:109], v[160:161], off
	v_lshl_add_u64 v[160:161], v[160:161], 0, s[80:81]
	global_load_dwordx4 v[110:113], v[160:161], off
	v_lshl_add_u64 v[160:161], v[160:161], 0, s[82:83]
	global_load_dwordx4 v[132:135], v[180:181], off
	v_lshl_add_u64 v[180:181], v[180:181], 0, s[80:81]
	global_load_dwordx4 v[136:139], v[180:181], off
	v_lshl_add_u64 v[180:181], v[180:181], 0, s[80:81]
	global_load_dwordx4 v[140:143], v[180:181], off
	v_lshl_add_u64 v[180:181], v[180:181], 0, s[80:81]
	global_load_dwordx4 v[144:147], v[180:181], off
	v_lshl_add_u64 v[180:181], v[180:181], 0, s[82:83]
	global_load_dwordx4 v[148:151], v[158:159], off offset:128
	v_lshl_add_u64 v[158:159], v[158:159], 0, s[80:81]
	global_load_dwordx4 v[166:169], v[158:159], off offset:128
	v_lshl_add_u64 v[158:159], v[158:159], 0, s[80:81]
	global_load_dwordx4 v[170:173], v[158:159], off offset:128
	v_lshl_add_u64 v[158:159], v[158:159], 0, s[80:81]
	global_load_dwordx4 v[174:177], v[158:159], off offset:128
	global_load_dwordx4 v[198:201], v[160:161], off offset:128
	v_lshl_add_u64 v[160:161], v[160:161], 0, s[80:81]
	global_load_dwordx4 v[202:205], v[160:161], off offset:128
	v_lshl_add_u64 v[160:161], v[160:161], 0, s[80:81]
	global_load_dwordx4 v[216:219], v[160:161], off offset:128
	v_lshl_add_u64 v[160:161], v[160:161], 0, s[80:81]
	global_load_dwordx4 v[220:223], v[160:161], off offset:128
	global_load_dwordx4 v[224:227], v[180:181], off offset:128
	v_lshl_add_u64 v[180:181], v[180:181], 0, s[80:81]
	global_load_dwordx4 v[228:231], v[180:181], off offset:128
	v_lshl_add_u64 v[180:181], v[180:181], 0, s[80:81]
	global_load_dwordx4 v[232:235], v[180:181], off offset:128
	v_lshl_add_u64 v[180:181], v[180:181], 0, s[80:81]
	global_load_dwordx4 v[236:239], v[180:181], off offset:128
	s_waitcnt vmcnt(16)
	ds_write_b128 v194, v[82:85]
	ds_write_b128 v195, v[86:89] offset:1024
	ds_write_b128 v194, v[90:93] offset:2048
	ds_write_b128 v195, v[94:97] offset:3072
	ds_write_b128 v194, v[98:101] offset:4096
	ds_write_b128 v195, v[102:105] offset:5120
	ds_write_b128 v194, v[106:109] offset:6144
	ds_write_b128 v195, v[110:113] offset:7168
	ds_read_b128 v[82:85], v244
	ds_read_b128 v[86:89], v245
	ds_read_b128 v[90:93], v246
	ds_read_b128 v[94:97], v193
	ds_read_b128 v[98:101], v244 offset:4096
	ds_read_b128 v[102:105], v245 offset:4096
	ds_read_b128 v[106:109], v246 offset:4096
	ds_read_b128 v[110:113], v193 offset:4096
	s_waitcnt lgkmcnt(0)
	v_mfma_f32_32x32x16_bf16 v[2:17], v[82:85], v[98:101], 0
	v_mfma_f32_32x32x16_bf16 v[2:17], v[86:89], v[102:105], v[2:17]
	v_mfma_f32_32x32x16_bf16 v[2:17], v[90:93], v[106:109], v[2:17]
	v_mfma_f32_32x32x16_bf16 v[2:17], v[94:97], v[110:113], v[2:17]
	s_waitcnt vmcnt(12)
	ds_write_b128 v194, v[132:135] offset:4096
	ds_write_b128 v195, v[136:139] offset:5120
	ds_write_b128 v194, v[140:143] offset:6144
	ds_write_b128 v195, v[144:147] offset:7168
	ds_read_b128 v[132:135], v244 offset:4096
	ds_read_b128 v[136:139], v245 offset:4096
	ds_read_b128 v[140:143], v246 offset:4096
	ds_read_b128 v[144:147], v193 offset:4096
	s_waitcnt lgkmcnt(0)
	v_mfma_f32_32x32x16_bf16 v[18:33], v[82:85], v[132:135], 0
	v_mfma_f32_32x32x16_bf16 v[18:33], v[86:89], v[136:139], v[18:33]
	v_mfma_f32_32x32x16_bf16 v[18:33], v[90:93], v[140:143], v[18:33]
	v_mfma_f32_32x32x16_bf16 v[18:33], v[94:97], v[144:147], v[18:33]
	s_waitcnt vmcnt(4)
	ds_write_b128 v194, v[148:151]
	ds_write_b128 v195, v[166:169] offset:1024
	ds_write_b128 v194, v[170:173] offset:2048
	ds_write_b128 v195, v[174:177] offset:3072
	ds_write_b128 v194, v[198:201] offset:4096
	ds_write_b128 v195, v[202:205] offset:5120
	ds_write_b128 v194, v[216:219] offset:6144
	ds_write_b128 v195, v[220:223] offset:7168
	ds_read_b128 v[148:151], v244
	ds_read_b128 v[166:169], v245
	ds_read_b128 v[170:173], v246
	ds_read_b128 v[174:177], v193
	ds_read_b128 v[198:201], v244 offset:4096
	ds_read_b128 v[202:205], v245 offset:4096
	ds_read_b128 v[216:219], v246 offset:4096
	ds_read_b128 v[220:223], v193 offset:4096
	s_waitcnt lgkmcnt(0)
	v_mfma_f32_32x32x16_bf16 v[2:17], v[148:151], v[198:201], v[2:17]
	v_mfma_f32_32x32x16_bf16 v[2:17], v[166:169], v[202:205], v[2:17]
	v_mfma_f32_32x32x16_bf16 v[2:17], v[170:173], v[216:219], v[2:17]
	v_mfma_f32_32x32x16_bf16 v[2:17], v[174:177], v[220:223], v[2:17]
	s_waitcnt vmcnt(0)
	ds_write_b128 v194, v[224:227] offset:4096
	ds_write_b128 v195, v[228:231] offset:5120
	ds_write_b128 v194, v[232:235] offset:6144
	ds_write_b128 v195, v[236:239] offset:7168
	ds_read_b128 v[224:227], v244 offset:4096
	ds_read_b128 v[228:231], v245 offset:4096
	ds_read_b128 v[232:235], v246 offset:4096
	ds_read_b128 v[236:239], v193 offset:4096
	s_waitcnt lgkmcnt(0)
	v_mfma_f32_32x32x16_bf16 v[18:33], v[148:151], v[224:227], v[18:33]
	v_mfma_f32_32x32x16_bf16 v[18:33], v[166:169], v[228:231], v[18:33]
	v_mfma_f32_32x32x16_bf16 v[18:33], v[170:173], v[232:235], v[18:33]
	v_mfma_f32_32x32x16_bf16 v[18:33], v[174:177], v[236:239], v[18:33]
	s_barrier
; #define LAS __attribute__((address_space(3)))
; DI float bflo(unsigned u) { return __uint_as_float(u << 16); }
; DI float bfhi(unsigned u) { return __uint_as_float(u & 0xffff0000u); }
; DI float red16(float v) { v += __shfl_xor(v, 1); v += __shfl_xor(v, 2); v += __shfl_xor(v, 4); v += __shfl_xor(v, 8); return v; }
; DI u32x2 pk4(const f32x4 a) { return (u32x2){pk2(a[0], a[1]), pk2(a[2], a[3])}; }
;     DI void operator()(const f32x4 v, int row, int pn, int wc, int bj, int cl) const {
;     ...
;         else { const u32x2 w = *(const u32x2*)(XN + (size_t)row * D + col); x = (f32x4){bflo(w.x), bfhi(w.x), bflo(w.y), bfhi(w.y)}; }
;         x += v;
;         if (MODE == 2) *(f32x4*)(out + (size_t)row * D + col) = x;
;         else {
;             *(u32x2*)(XN + (size_t)row * D + col) = pk4(x);
;             const float ssq = red16((x[0] * x[0] + x[1] * x[1]) + (x[2] * x[2] + x[3] * x[3]));
;             if ((threadIdx.x & 15) == 0) atomicAdd(SS + row, ssq);
; template <class EpiS>
; DI void sample_gemm(LAS unsigned char* lds, const bf16_t* A, const bf16_t* Bt, int nN, int K, const EpiS& E) {
;     ...
;         __syncthreads();
;         LAS float* part = (LAS float*)(lds + w * 8192);
; #pragma unroll
;         for (int r = 0; r < 16; ++r) { const int row = (r & 3) + 8 * (r >> 2) + 4 * h; part[row * 64 + r32] = c0[r]; part[row * 64 + 32 + r32] = c1[r]; }
;         __syncthreads();
;         f32x4 v = (f32x4){0.f, 0.f, 0.f, 0.f};
; #pragma unroll
;         for (int ww = 0; ww < 8; ++ww) v += *(const LAS f32x4*)(lds + ww * 8192 + (tid >> 4) * 256 + (tid & 15) * 16);
;         E(v, MP + rb * 32 + (tid >> 4), pn, wc, (tid >> 3) & 1, 4 * (tid & 7));
	s_nop 11
	ds_write2_b32 v41, v2, v18 offset1:32
	ds_write2_b32 v41, v3, v19 offset0:64 offset1:96
	ds_write2_b32 v41, v4, v20 offset0:128 offset1:160
	ds_write2_b32 v41, v5, v21 offset0:192 offset1:224
	ds_write2_b32 v48, v6, v22 offset1:32
	ds_write2_b32 v48, v7, v23 offset0:64 offset1:96
	ds_write2_b32 v48, v8, v24 offset0:128 offset1:160
	ds_write2_b32 v48, v9, v25 offset0:192 offset1:224
	ds_write2_b32 v49, v10, v26 offset1:32
	ds_write2_b32 v49, v11, v27 offset0:64 offset1:96
	ds_write2_b32 v49, v12, v28 offset0:128 offset1:160
	ds_write2_b32 v49, v13, v29 offset0:192 offset1:224
	ds_write2_b32 v50, v14, v30 offset1:32
	ds_write2_b32 v50, v15, v31 offset0:64 offset1:96
	ds_write2_b32 v50, v16, v32 offset0:128 offset1:160
	ds_write2_b32 v50, v17, v33 offset0:192 offset1:224
	s_waitcnt lgkmcnt(0)
	s_barrier
	ds_read_b128 v[2:5], v47
	ds_read_b128 v[6:9], v47 offset:8192
	ds_read_b128 v[10:13], v47 offset:16384
	ds_read_b128 v[14:17], v47 offset:24576
	ds_read_b128 v[18:21], v47 offset:32768
	ds_read_b128 v[22:25], v47 offset:40960
	ds_read_b128 v[26:29], v47 offset:49152
	ds_read_b128 v[30:33], v47 offset:57344
	s_waitcnt lgkmcnt(7)
	v_pk_add_f32 v[4:5], v[4:5], 0 op_sel_hi:[1,0]
	v_pk_add_f32 v[2:3], v[2:3], 0 op_sel_hi:[1,0]
	s_waitcnt lgkmcnt(6)
	v_pk_add_f32 v[4:5], v[4:5], v[8:9]
	v_pk_add_f32 v[2:3], v[2:3], v[6:7]
	s_waitcnt lgkmcnt(5)
	v_pk_add_f32 v[4:5], v[4:5], v[12:13]
	v_pk_add_f32 v[2:3], v[2:3], v[10:11]
	s_waitcnt lgkmcnt(4)
	v_pk_add_f32 v[4:5], v[4:5], v[16:17]
	v_pk_add_f32 v[2:3], v[2:3], v[14:15]
	s_waitcnt lgkmcnt(3)
	v_pk_add_f32 v[4:5], v[4:5], v[20:21]
	v_pk_add_f32 v[2:3], v[2:3], v[18:19]
	s_waitcnt lgkmcnt(2)
	v_pk_add_f32 v[4:5], v[4:5], v[24:25]
	v_pk_add_f32 v[2:3], v[2:3], v[22:23]
	s_waitcnt lgkmcnt(1)
	v_pk_add_f32 v[4:5], v[4:5], v[28:29]
	v_pk_add_f32 v[2:3], v[2:3], v[26:27]
	s_waitcnt lgkmcnt(0)
	v_pk_add_f32 v[4:5], v[4:5], v[32:33]
	v_pk_add_f32 v[2:3], v[2:3], v[30:31]
	s_waitcnt vmcnt(0)
	v_lshlrev_b32_e32 v6, 16, v240
	v_and_b32_e32 v7, 0xffff0000, v240
	v_lshlrev_b32_e32 v8, 16, v241
	v_and_b32_e32 v9, 0xffff0000, v241
	v_pk_add_f32 v[4:5], v[4:5], v[8:9]
	v_pk_add_f32 v[6:7], v[2:3], v[6:7]
	v_mul_f32_e32 v3, v5, v5
	v_mul_f32_e32 v2, v7, v7
	v_fmac_f32_e32 v2, v6, v6
	v_fmac_f32_e32 v3, v4, v4
	v_add_f32_e32 v2, v2, v3
	ds_bpermute_b32 v3, v43, v2
	v_cvt_pk_bf16_f32 v6, v6, v7
	v_cvt_pk_bf16_f32 v7, v4, v5
	global_store_dwordx2 v[56:57], v[6:7], off
	s_waitcnt lgkmcnt(0)
	v_add_f32_e32 v2, v2, v3
	ds_bpermute_b32 v3, v44, v2
	s_waitcnt lgkmcnt(0)
	v_add_f32_e32 v2, v2, v3
	ds_bpermute_b32 v3, v45, v2
	s_waitcnt lgkmcnt(0)
	v_add_f32_e32 v2, v2, v3
	ds_bpermute_b32 v3, v46, v2
	s_and_saveexec_b64 s[0:1], vcc
	s_cbranch_execz .LBB0_1364
	s_waitcnt lgkmcnt(0)
	v_add_f32_e32 v2, v2, v3
	v_lshlrev_b32_e32 v3, 2, v51
	global_atomic_add_f32 v3, v2, s[8:9]
	s_branch .LBB0_1364

; DI float row_rstd(const float* SS, int row) { return rsqrtf(SS[row] * (1.0f / 1024.0f) + 1e-6f); }
;     DI void operator()(const f32x4 v, int row, int pn, int wc, int bj, int cl) const {
;         const float rs = row_rstd(SS, row);
; template <class EpiS>
; DI void sample_gemm(LAS unsigned char* lds, const bf16_t* A, const bf16_t* Bt, int nN, int K, const EpiS& E) {
;     ...
;     for (int un = (int)blockIdx.x; un < nunits; un += (int)gridDim.x) {
;         const int rb = un & 3, wc = (un >> 2) & 3, pn = un >> 4;
;         const bf16_t* ap = A + (size_t)(MP + rb * 32 + r32) * K + w * kw + h * 8;
;         const bf16_t* b0p = Bt + (size_t)(pn * 256 + wc * 32 + r32) * K + w * kw + h * 8;
;         const bf16_t* b1p = b0p + (size_t)128 * K;
;         f32x16 c0, c1;
; #pragma unroll
;         for (int r = 0; r < 16; ++r) { c0[r] = 0.f; c1[r] = 0.f; }
; #pragma unroll 8
;         for (int ks = 0; ks < nk; ++ks) {
;             const bf16x8 a = *(const bf16x8*)(ap + ks * 16), b0 = *(const bf16x8*)(b0p + ks * 16), b1 = *(const bf16x8*)(b1p + ks * 16);
;             c0 = __builtin_amdgcn_mfma_f32_32x32x16_bf16(a, b0, c0, 0, 0, 0);
;             c1 = __builtin_amdgcn_mfma_f32_32x32x16_bf16(a, b1, c1, 0, 0, 0);
;         }
.LBB0_1438:
	s_and_b32 s16, s10, 0x60
	s_bitset1_b32 s16, 15
	s_ashr_i32 s4, s14, 4
	s_waitcnt lgkmcnt(2)
	v_or_b32_e32 v3, s16, v42
	s_lshl_b32 s0, s4, 8
	s_and_b32 s15, s8, 0x60
	v_lshlrev_b32_e32 v34, 11, v3
	s_or_b32 s0, s0, s15
	v_lshl_add_u64 v[74:75], v[36:37], 0, v[34:35]
	v_or_b32_e32 v2, s0, v42
	v_ashrrev_i32_e32 v3, 31, v2
	v_lshlrev_b64 v[2:3], 11, v[2:3]
	v_lshl_add_u64 v[76:77], v[38:39], 0, v[2:3]
	s_waitcnt lgkmcnt(0)
	v_add_co_u32_e64 v78, s[0:1], s12, v76
	v_addc_co_u32_e64 v79, s[0:1], 0, v77, s[0:1]
	v_add_u32_e32 v240, s16, v1
	v_lshlrev_b32_e32 v240, 2, v240
	global_load_dword v240, v240, s[20:21]
	v_lshl_add_u64 v[158:159], v[74:75], 0, v[182:183]
	v_lshl_add_u64 v[160:161], v[76:77], 0, v[182:183]
	v_lshl_add_u64 v[180:181], v[78:79], 0, v[182:183]
	global_load_dwordx4 v[82:85], v[158:159], off
	v_lshl_add_u64 v[158:159], v[158:159], 0, s[80:81]
	global_load_dwordx4 v[86:89], v[158:159], off
	v_lshl_add_u64 v[158:159], v[158:159], 0, s[80:81]
	global_load_dwordx4 v[90:93], v[158:159], off
	v_lshl_add_u64 v[158:159], v[158:159], 0, s[80:81]
	global_load_dwordx4 v[94:97], v[158:159], off
	v_lshl_add_u64 v[158:159], v[158:159], 0, s[82:83]
	global_load_dwordx4 v[98:101], v[160:161], off
	v_lshl_add_u64 v[160:161], v[160:161], 0, s[80:81]
	global_load_dwordx4 v[102:105], v[160:161], off
	v_lshl_add_u64 v[160:161], v[160:161], 0, s[80:81]
	global_load_dwordx4 v[106:109], v[160:161], off
	v_lshl_add_u64 v[160:161], v[160:161], 0, s[80:81]
	global_load_dwordx4 v[110:113], v[160:161], off
	v_lshl_add_u64 v[160:161], v[160:161], 0, s[82:83]
	global_load_dwordx4 v[132:135], v[180:181], off
	v_lshl_add_u64 v[180:181], v[180:181], 0, s[80:81]
	global_load_dwordx4 v[136:139], v[180:181], off
	v_lshl_add_u64 v[180:181], v[180:181], 0, s[80:81]
	global_load_dwordx4 v[140:143], v[180:181], off
	v_lshl_add_u64 v[180:181], v[180:181], 0, s[80:81]
	global_load_dwordx4 v[144:147], v[180:181], off
	v_lshl_add_u64 v[180:181], v[180:181], 0, s[82:83]
	global_load_dwordx4 v[148:151], v[158:159], off offset:128
	v_lshl_add_u64 v[158:159], v[158:159], 0, s[80:81]
	global_load_dwordx4 v[166:169], v[158:159], off offset:128
	v_lshl_add_u64 v[158:159], v[158:159], 0, s[80:81]
	global_load_dwordx4 v[170:173], v[158:159], off offset:128
	v_lshl_add_u64 v[158:159], v[158:159], 0, s[80:81]
	global_load_dwordx4 v[174:177], v[158:159], off offset:128
	global_load_dwordx4 v[198:201], v[160:161], off offset:128
	v_lshl_add_u64 v[160:161], v[160:161], 0, s[80:81]
	global_load_dwordx4 v[202:205], v[160:161], off offset:128
	v_lshl_add_u64 v[160:161], v[160:161], 0, s[80:81]
	global_load_dwordx4 v[216:219], v[160:161], off offset:128
	v_lshl_add_u64 v[160:161], v[160:161], 0, s[80:81]
	global_load_dwordx4 v[220:223], v[160:161], off offset:128
	global_load_dwordx4 v[224:227], v[180:181], off offset:128
	v_lshl_add_u64 v[180:181], v[180:181], 0, s[80:81]
	global_load_dwordx4 v[228:231], v[180:181], off offset:128
	v_lshl_add_u64 v[180:181], v[180:181], 0, s[80:81]
	global_load_dwordx4 v[232:235], v[180:181], off offset:128
	v_lshl_add_u64 v[180:181], v[180:181], 0, s[80:81]
	global_load_dwordx4 v[236:239], v[180:181], off offset:128
	s_waitcnt vmcnt(16)
	ds_write_b128 v194, v[82:85]
	ds_write_b128 v195, v[86:89] offset:1024
	ds_write_b128 v194, v[90:93] offset:2048
	ds_write_b128 v195, v[94:97] offset:3072
	ds_write_b128 v194, v[98:101] offset:4096
	ds_write_b128 v195, v[102:105] offset:5120
	ds_write_b128 v194, v[106:109] offset:6144
	ds_write_b128 v195, v[110:113] offset:7168
	ds_read_b128 v[82:85], v244
	ds_read_b128 v[86:89], v245
	ds_read_b128 v[90:93], v246
	ds_read_b128 v[94:97], v193
	ds_read_b128 v[98:101], v244 offset:4096
	ds_read_b128 v[102:105], v245 offset:4096
	ds_read_b128 v[106:109], v246 offset:4096
	ds_read_b128 v[110:113], v193 offset:4096
	s_waitcnt lgkmcnt(0)
	v_mfma_f32_32x32x16_bf16 v[2:17], v[82:85], v[98:101], 0
	v_mfma_f32_32x32x16_bf16 v[2:17], v[86:89], v[102:105], v[2:17]
	v_mfma_f32_32x32x16_bf16 v[2:17], v[90:93], v[106:109], v[2:17]
	v_mfma_f32_32x32x16_bf16 v[2:17], v[94:97], v[110:113], v[2:17]
	s_waitcnt vmcnt(12)
	ds_write_b128 v194, v[132:135] offset:4096
	ds_write_b128 v195, v[136:139] offset:5120
	ds_write_b128 v194, v[140:143] offset:6144
	ds_write_b128 v195, v[144:147] offset:7168
	ds_read_b128 v[132:135], v244 offset:4096
	ds_read_b128 v[136:139], v245 offset:4096
	ds_read_b128 v[140:143], v246 offset:4096
	ds_read_b128 v[144:147], v193 offset:4096
	s_waitcnt lgkmcnt(0)
	v_mfma_f32_32x32x16_bf16 v[18:33], v[82:85], v[132:135], 0
	v_mfma_f32_32x32x16_bf16 v[18:33], v[86:89], v[136:139], v[18:33]
	v_mfma_f32_32x32x16_bf16 v[18:33], v[90:93], v[140:143], v[18:33]
	v_mfma_f32_32x32x16_bf16 v[18:33], v[94:97], v[144:147], v[18:33]
	s_waitcnt vmcnt(4)
	ds_write_b128 v194, v[148:151]
	ds_write_b128 v195, v[166:169] offset:1024
	ds_write_b128 v194, v[170:173] offset:2048
	ds_write_b128 v195, v[174:177] offset:3072
	ds_write_b128 v194, v[198:201] offset:4096
	ds_write_b128 v195, v[202:205] offset:5120
	ds_write_b128 v194, v[216:219] offset:6144
	ds_write_b128 v195, v[220:223] offset:7168
	ds_read_b128 v[148:151], v244
	ds_read_b128 v[166:169], v245
	ds_read_b128 v[170:173], v246
	ds_read_b128 v[174:177], v193
	ds_read_b128 v[198:201], v244 offset:4096
	ds_read_b128 v[202:205], v245 offset:4096
	ds_read_b128 v[216:219], v246 offset:4096
	ds_read_b128 v[220:223], v193 offset:4096
	s_waitcnt lgkmcnt(0)
	v_mfma_f32_32x32x16_bf16 v[2:17], v[148:151], v[198:201], v[2:17]
	v_mfma_f32_32x32x16_bf16 v[2:17], v[166:169], v[202:205], v[2:17]
	v_mfma_f32_32x32x16_bf16 v[2:17], v[170:173], v[216:219], v[2:17]
	v_mfma_f32_32x32x16_bf16 v[2:17], v[174:177], v[220:223], v[2:17]
	s_waitcnt vmcnt(0)
	ds_write_b128 v194, v[224:227] offset:4096
	ds_write_b128 v195, v[228:231] offset:5120
	ds_write_b128 v194, v[232:235] offset:6144
	ds_write_b128 v195, v[236:239] offset:7168
	ds_read_b128 v[224:227], v244 offset:4096
	ds_read_b128 v[228:231], v245 offset:4096
	ds_read_b128 v[232:235], v246 offset:4096
	ds_read_b128 v[236:239], v193 offset:4096
	s_waitcnt lgkmcnt(0)
	v_mfma_f32_32x32x16_bf16 v[18:33], v[148:151], v[224:227], v[18:33]
	v_mfma_f32_32x32x16_bf16 v[18:33], v[166:169], v[228:231], v[18:33]
	v_mfma_f32_32x32x16_bf16 v[18:33], v[170:173], v[232:235], v[18:33]
	v_mfma_f32_32x32x16_bf16 v[18:33], v[174:177], v[236:239], v[18:33]
	s_barrier
; #define LAS __attribute__((address_space(3)))
; DI float sigmoidf_(float x) { return __builtin_amdgcn_rcpf(1.0f + __expf(-x)); }
; DI float row_rstd(const float* SS, int row) { return rsqrtf(SS[row] * (1.0f / 1024.0f) + 1e-6f); }
; DI f32x4 shx8(const f32x4 v) { f32x4 o; o[0] = __shfl_xor(v[0], 8); o[1] = __shfl_xor(v[1], 8); o[2] = __shfl_xor(v[2], 8); o[3] = __shfl_xor(v[3], 8); return o; }
; DI u32x2 pk4(const f32x4 a) { return (u32x2){pk2(a[0], a[1]), pk2(a[2], a[3])}; }
;     DI void operator()(const f32x4 v, int row, int pn, int wc, int bj, int cl) const {
;         const float rs = row_rstd(SS, row);
;         const f32x4 o = shx8(v);
;         if (bj == 0) {
;             f32x4 hv;
; #pragma unroll
;             for (int i = 0; i < 4; ++i) { const float g0 = v[i] * rs; hv[i] = g0 * sigmoidf_(g0) * (o[i] * rs); }
;             *(u32x2*)(HID + (size_t)row * FH + pn * 128 + wc * 32 + cl) = pk4(hv);
; template <class EpiS>
; DI void sample_gemm(LAS unsigned char* lds, const bf16_t* A, const bf16_t* Bt, int nN, int K, const EpiS& E) {
;     ...
;         __syncthreads();
;         LAS float* part = (LAS float*)(lds + w * 8192);
; #pragma unroll
;         for (int r = 0; r < 16; ++r) { const int row = (r & 3) + 8 * (r >> 2) + 4 * h; part[row * 64 + r32] = c0[r]; part[row * 64 + 32 + r32] = c1[r]; }
;         __syncthreads();
;         f32x4 v = (f32x4){0.f, 0.f, 0.f, 0.f};
; #pragma unroll
;         for (int ww = 0; ww < 8; ++ww) v += *(const LAS f32x4*)(lds + ww * 8192 + (tid >> 4) * 256 + (tid & 15) * 16);
;         E(v, MP + rb * 32 + (tid >> 4), pn, wc, (tid >> 3) & 1, 4 * (tid & 7));
	s_nop 11
	ds_write2_b32 v44, v2, v18 offset1:32
	ds_write2_b32 v44, v3, v19 offset0:64 offset1:96
	ds_write2_b32 v44, v4, v20 offset0:128 offset1:160
	ds_write2_b32 v44, v5, v21 offset0:192 offset1:224
	ds_write2_b32 v47, v6, v22 offset1:32
	ds_write2_b32 v47, v7, v23 offset0:64 offset1:96
	ds_write2_b32 v47, v8, v24 offset0:128 offset1:160
	ds_write2_b32 v47, v9, v25 offset0:192 offset1:224
	ds_write2_b32 v48, v10, v26 offset1:32
	ds_write2_b32 v48, v11, v27 offset0:64 offset1:96
	ds_write2_b32 v48, v12, v28 offset0:128 offset1:160
	ds_write2_b32 v48, v13, v29 offset0:192 offset1:224
	ds_write2_b32 v49, v14, v30 offset1:32
	ds_write2_b32 v49, v15, v31 offset0:64 offset1:96
	ds_write2_b32 v49, v16, v32 offset0:128 offset1:160
	ds_write2_b32 v49, v17, v33 offset0:192 offset1:224
	s_waitcnt lgkmcnt(0)
	s_barrier
	ds_read_b128 v[2:5], v45
	ds_read_b128 v[6:9], v45 offset:8192
	ds_read_b128 v[10:13], v45 offset:16384
	ds_read_b128 v[14:17], v45 offset:24576
	ds_read_b128 v[18:21], v45 offset:32768
	ds_read_b128 v[22:25], v45 offset:40960
	ds_read_b128 v[26:29], v45 offset:49152
	ds_read_b128 v[30:33], v45 offset:57344
	s_waitcnt lgkmcnt(7)
	v_pk_add_f32 v[4:5], v[4:5], 0 op_sel_hi:[1,0]
	v_pk_add_f32 v[2:3], v[2:3], 0 op_sel_hi:[1,0]
	s_waitcnt lgkmcnt(6)
	v_pk_add_f32 v[4:5], v[4:5], v[8:9]
	v_pk_add_f32 v[2:3], v[2:3], v[6:7]
	s_waitcnt lgkmcnt(5)
	v_pk_add_f32 v[4:5], v[4:5], v[12:13]
	v_pk_add_f32 v[2:3], v[2:3], v[10:11]
	s_waitcnt lgkmcnt(4)
	v_pk_add_f32 v[4:5], v[4:5], v[16:17]
	v_pk_add_f32 v[2:3], v[2:3], v[14:15]
	s_waitcnt lgkmcnt(3)
	v_pk_add_f32 v[4:5], v[4:5], v[20:21]
	v_pk_add_f32 v[2:3], v[2:3], v[18:19]
	s_waitcnt lgkmcnt(2)
	v_pk_add_f32 v[4:5], v[4:5], v[24:25]
	v_pk_add_f32 v[2:3], v[2:3], v[22:23]
	s_waitcnt lgkmcnt(1)
	v_pk_add_f32 v[4:5], v[4:5], v[28:29]
	v_pk_add_f32 v[2:3], v[2:3], v[26:27]
	s_waitcnt lgkmcnt(0)
	v_pk_add_f32 v[6:7], v[4:5], v[32:33]
	v_pk_add_f32 v[8:9], v[2:3], v[30:31]
	ds_bpermute_b32 v2, v43, v8
	ds_bpermute_b32 v3, v43, v9
	ds_bpermute_b32 v4, v43, v6
	ds_bpermute_b32 v5, v43, v7
	s_and_saveexec_b64 s[6:7], vcc
	s_cbranch_execz .LBB0_1437
	v_add_u32_e32 v10, s16, v1
	v_mul_u32_u24_e32 v10, 0xb00, v10
	v_lshlrev_b32_e32 v34, 1, v10
	s_lshl_b32 s16, s4, 7
	s_ashr_i32 s17, s16, 31
	s_lshl_b32 s4, s15, 1
	v_mov_b32_e32 v41, v35
	s_waitcnt vmcnt(0)
	v_fmamk_f32 v10, v240, 0x3a800000, v46
	v_mul_f32_e32 v11, 0x4b800000, v10
	v_cmp_gt_f32_e64 s[0:1], s13, v10
	s_nop 1
	v_cndmask_b32_e64 v10, v10, v11, s[0:1]
	v_rsq_f32_e32 v12, v10
	v_lshl_add_u64 v[10:11], s[24:25], 0, v[34:35]
	v_lshl_add_u64 v[10:11], s[16:17], 1, v[10:11]
	v_lshl_add_u64 v[10:11], v[10:11], 0, s[4:5]
	v_mul_f32_e32 v13, 0x45800000, v12
	v_cndmask_b32_e64 v12, v12, v13, s[0:1]
	v_pk_mul_f32 v[8:9], v[8:9], v[12:13] op_sel_hi:[1,0]
	v_pk_mul_f32 v[6:7], v[6:7], v[12:13] op_sel_hi:[1,0]
	v_mul_f32_e32 v13, 0xbfb8aa3b, v8
	v_mul_f32_e32 v14, 0xbfb8aa3b, v9
	v_mul_f32_e32 v15, 0xbfb8aa3b, v6
	v_mul_f32_e32 v16, 0xbfb8aa3b, v7
	v_exp_f32_e32 v13, v13
	v_exp_f32_e32 v14, v14
	v_exp_f32_e32 v15, v15
	v_exp_f32_e32 v16, v16
	v_add_f32_e32 v13, 1.0, v13
	v_add_f32_e32 v17, 1.0, v14
	v_add_f32_e32 v18, 1.0, v15
	v_add_f32_e32 v19, 1.0, v16
	v_rcp_f32_e32 v14, v13
	v_rcp_f32_e32 v15, v17
	v_rcp_f32_e32 v16, v18
	v_rcp_f32_e32 v17, v19
	s_waitcnt lgkmcnt(2)
	v_pk_mul_f32 v[2:3], v[12:13], v[2:3] op_sel_hi:[0,1]
	s_waitcnt lgkmcnt(0)
	v_pk_mul_f32 v[4:5], v[12:13], v[4:5] op_sel_hi:[0,1]
	v_pk_mul_f32 v[8:9], v[8:9], v[14:15]
	v_pk_mul_f32 v[6:7], v[6:7], v[16:17]
	v_pk_mul_f32 v[2:3], v[2:3], v[8:9]
	v_pk_mul_f32 v[4:5], v[4:5], v[6:7]
	v_cvt_pk_bf16_f32 v2, v2, v3
	v_cvt_pk_bf16_f32 v3, v4, v5
	v_lshl_add_u64 v[4:5], v[10:11], 0, v[40:41]
	global_store_dwordx2 v[4:5], v[2:3], off
	s_branch .LBB0_1437

; DI float bflo(unsigned u) { return __uint_as_float(u << 16); }
; DI float bfhi(unsigned u) { return __uint_as_float(u & 0xffff0000u); }
;     DI void operator()(const f32x4 v, int row, int pn, int wc, int bj, int cl) const {
;     ...
;         else { const u32x2 w = *(const u32x2*)(XN + (size_t)row * D + col); x = (f32x4){bflo(w.x), bfhi(w.x), bflo(w.y), bfhi(w.y)}; }
; template <class EpiS>
; DI void sample_gemm(LAS unsigned char* lds, const bf16_t* A, const bf16_t* Bt, int nN, int K, const EpiS& E) {
;     ...
;     for (int un = (int)blockIdx.x; un < nunits; un += (int)gridDim.x) {
;         const int rb = un & 3, wc = (un >> 2) & 3, pn = un >> 4;
;         const bf16_t* ap = A + (size_t)(MP + rb * 32 + r32) * K + w * kw + h * 8;
;         const bf16_t* b0p = Bt + (size_t)(pn * 256 + wc * 32 + r32) * K + w * kw + h * 8;
;         const bf16_t* b1p = b0p + (size_t)128 * K;
;         f32x16 c0, c1;
; #pragma unroll
;         for (int r = 0; r < 16; ++r) { c0[r] = 0.f; c1[r] = 0.f; }
; #pragma unroll 8
;         for (int ks = 0; ks < nk; ++ks) {
;             const bf16x8 a = *(const bf16x8*)(ap + ks * 16), b0 = *(const bf16x8*)(b0p + ks * 16), b1 = *(const bf16x8*)(b1p + ks * 16);
;             c0 = __builtin_amdgcn_mfma_f32_32x32x16_bf16(a, b0, c0, 0, 0, 0);
;             c1 = __builtin_amdgcn_mfma_f32_32x32x16_bf16(a, b1, c1, 0, 0, 0);
;         }
.LBB0_1522:
	s_and_b32 s11, s4, 0xffffff00
	s_and_b32 s12, s0, 0x60
	s_and_b32 s10, s6, 0x60
	s_or_b32 s11, s11, s12
	s_bitset1_b32 s10, 15
	v_or_b32_e32 v1, s11, v38
	v_or_b32_e32 v0, s10, v38
	v_mad_i64_i32 v[70:71], s[12:13], v1, s8, v[36:37]
	v_mul_u32_u24_e32 v0, 0xb00, v0
	v_add_co_u32_e32 v72, vcc, s9, v70
	v_lshlrev_b32_e32 v32, 1, v0
	s_nop 0
	v_addc_co_u32_e32 v73, vcc, 0, v71, vcc
	v_lshl_add_u64 v[74:75], v[34:35], 0, v[32:33]
	s_add_i32 s2, s2, s3
	s_add_i32 s0, s0, s1
	s_add_i32 s4, s4, s5
	s_add_i32 s6, s6, s7
	s_cmp_lt_i32 s2, 64
	v_add_u32_e32 v60, s10, v40
	v_or_b32_e32 v58, s11, v41
	v_lshlrev_b32_e32 v32, 11, v60
	v_ashrrev_i32_e32 v59, 31, v58
	v_lshl_add_u64 v[50:51], s[34:35], 0, v[32:33]
	v_lshl_add_u64 v[50:51], v[58:59], 1, v[50:51]
	v_lshlrev_b32_e32 v32, 12, v60
	global_load_dwordx2 v[208:209], v[50:51], off
	v_lshl_add_u64 v[240:241], v[74:75], 0, v[182:183]
	v_lshl_add_u64 v[242:243], v[240:241], 0, s[80:81]
	v_lshl_add_u64 v[248:249], v[70:71], 0, v[182:183]
	v_lshl_add_u64 v[250:251], v[248:249], 0, s[80:81]
	v_lshl_add_u64 v[252:253], v[72:73], 0, v[182:183]
	v_lshl_add_u64 v[254:255], v[252:253], 0, s[80:81]
	global_load_dwordx4 v[82:85], v[240:241], off
	global_load_dwordx4 v[86:89], v[242:243], off
	global_load_dwordx4 v[90:93], v[248:249], off
	global_load_dwordx4 v[94:97], v[250:251], off
	global_load_dwordx4 v[98:101], v[252:253], off
	global_load_dwordx4 v[102:105], v[254:255], off
	global_load_dwordx4 v[106:109], v[240:241], off offset:64
	global_load_dwordx4 v[110:113], v[242:243], off offset:64
	global_load_dwordx4 v[132:135], v[248:249], off offset:64
	global_load_dwordx4 v[136:139], v[250:251], off offset:64
	global_load_dwordx4 v[140:143], v[252:253], off offset:64
	global_load_dwordx4 v[144:147], v[254:255], off offset:64
	global_load_dwordx4 v[148:151], v[240:241], off offset:128
	global_load_dwordx4 v[166:169], v[242:243], off offset:128
	global_load_dwordx4 v[170:173], v[248:249], off offset:128
	global_load_dwordx4 v[174:177], v[250:251], off offset:128
	global_load_dwordx4 v[198:201], v[252:253], off offset:128
	global_load_dwordx4 v[202:205], v[254:255], off offset:128
	global_load_dwordx4 v[216:219], v[240:241], off offset:192
	global_load_dwordx4 v[220:223], v[242:243], off offset:192
	global_load_dwordx4 v[224:227], v[248:249], off offset:192
	global_load_dwordx4 v[228:231], v[250:251], off offset:192
	global_load_dwordx4 v[232:235], v[252:253], off offset:192
	global_load_dwordx4 v[236:239], v[254:255], off offset:192
	s_waitcnt vmcnt(18)
	ds_write_b128 v194, v[82:85]
	ds_write_b128 v194, v[86:89] offset:1024
	ds_write_b128 v194, v[90:93] offset:2048
	ds_write_b128 v194, v[94:97] offset:3072
	ds_write_b128 v194, v[98:101] offset:4096
	ds_write_b128 v194, v[102:105] offset:5120
	ds_read_b128 v[82:85], v244
	ds_read_b128 v[86:89], v245
	ds_read_b128 v[90:93], v244 offset:2048
	ds_read_b128 v[94:97], v245 offset:2048
	ds_read_b128 v[98:101], v244 offset:4096
	ds_read_b128 v[102:105], v245 offset:4096
	s_waitcnt lgkmcnt(0)
	v_mfma_f32_32x32x16_bf16 v[0:15], v[82:85], v[90:93], 0
	v_mfma_f32_32x32x16_bf16 v[0:15], v[86:89], v[94:97], v[0:15]
	v_mfma_f32_32x32x16_bf16 v[16:31], v[82:85], v[98:101], 0
	v_mfma_f32_32x32x16_bf16 v[16:31], v[86:89], v[102:105], v[16:31]
	global_load_dwordx4 v[82:85], v[240:241], off offset:256
	global_load_dwordx4 v[86:89], v[242:243], off offset:256
	global_load_dwordx4 v[90:93], v[248:249], off offset:256
	global_load_dwordx4 v[94:97], v[250:251], off offset:256
	global_load_dwordx4 v[98:101], v[252:253], off offset:256
	global_load_dwordx4 v[102:105], v[254:255], off offset:256
	s_waitcnt vmcnt(18)
	ds_write_b128 v194, v[106:109]
	ds_write_b128 v194, v[110:113] offset:1024
	ds_write_b128 v194, v[132:135] offset:2048
	ds_write_b128 v194, v[136:139] offset:3072
	ds_write_b128 v194, v[140:143] offset:4096
	ds_write_b128 v194, v[144:147] offset:5120
	ds_read_b128 v[106:109], v244
	ds_read_b128 v[110:113], v245
	ds_read_b128 v[132:135], v244 offset:2048
	ds_read_b128 v[136:139], v245 offset:2048
	ds_read_b128 v[140:143], v244 offset:4096
	ds_read_b128 v[144:147], v245 offset:4096
	s_waitcnt lgkmcnt(0)
	v_mfma_f32_32x32x16_bf16 v[0:15], v[106:109], v[132:135], v[0:15]
	v_mfma_f32_32x32x16_bf16 v[0:15], v[110:113], v[136:139], v[0:15]
	v_mfma_f32_32x32x16_bf16 v[16:31], v[106:109], v[140:143], v[16:31]
	v_mfma_f32_32x32x16_bf16 v[16:31], v[110:113], v[144:147], v[16:31]
	global_load_dwordx4 v[106:109], v[240:241], off offset:320
	global_load_dwordx4 v[110:113], v[242:243], off offset:320
	global_load_dwordx4 v[132:135], v[248:249], off offset:320
	global_load_dwordx4 v[136:139], v[250:251], off offset:320
	global_load_dwordx4 v[140:143], v[252:253], off offset:320
	global_load_dwordx4 v[144:147], v[254:255], off offset:320
	s_waitcnt vmcnt(18)
	ds_write_b128 v194, v[148:151]
	ds_write_b128 v194, v[166:169] offset:1024
	ds_write_b128 v194, v[170:173] offset:2048
	ds_write_b128 v194, v[174:177] offset:3072
	ds_write_b128 v194, v[198:201] offset:4096
	ds_write_b128 v194, v[202:205] offset:5120
	ds_read_b128 v[148:151], v244
	ds_read_b128 v[166:169], v245
	ds_read_b128 v[170:173], v244 offset:2048
	ds_read_b128 v[174:177], v245 offset:2048
	ds_read_b128 v[198:201], v244 offset:4096
	ds_read_b128 v[202:205], v245 offset:4096
	s_waitcnt lgkmcnt(0)
; template <class EpiS>
; DI void sample_gemm(LAS unsigned char* lds, const bf16_t* A, const bf16_t* Bt, int nN, int K, const EpiS& E) {
;     ...
; #pragma unroll 8
;         for (int ks = 0; ks < nk; ++ks) {
;             const bf16x8 a = *(const bf16x8*)(ap + ks * 16), b0 = *(const bf16x8*)(b0p + ks * 16), b1 = *(const bf16x8*)(b1p + ks * 16);
;             c0 = __builtin_amdgcn_mfma_f32_32x32x16_bf16(a, b0, c0, 0, 0, 0);
;             c1 = __builtin_amdgcn_mfma_f32_32x32x16_bf16(a, b1, c1, 0, 0, 0);
;         }
	v_mfma_f32_32x32x16_bf16 v[0:15], v[148:151], v[170:173], v[0:15]
	v_mfma_f32_32x32x16_bf16 v[0:15], v[166:169], v[174:177], v[0:15]
	v_mfma_f32_32x32x16_bf16 v[16:31], v[148:151], v[198:201], v[16:31]
	v_mfma_f32_32x32x16_bf16 v[16:31], v[166:169], v[202:205], v[16:31]
	global_load_dwordx4 v[148:151], v[240:241], off offset:384
	global_load_dwordx4 v[166:169], v[242:243], off offset:384
	global_load_dwordx4 v[170:173], v[248:249], off offset:384
	global_load_dwordx4 v[174:177], v[250:251], off offset:384
	global_load_dwordx4 v[198:201], v[252:253], off offset:384
	global_load_dwordx4 v[202:205], v[254:255], off offset:384
	s_waitcnt vmcnt(18)
	ds_write_b128 v194, v[216:219]
	ds_write_b128 v194, v[220:223] offset:1024
	ds_write_b128 v194, v[224:227] offset:2048
	ds_write_b128 v194, v[228:231] offset:3072
	ds_write_b128 v194, v[232:235] offset:4096
	ds_write_b128 v194, v[236:239] offset:5120
	ds_read_b128 v[216:219], v244
	ds_read_b128 v[220:223], v245
	ds_read_b128 v[224:227], v244 offset:2048
	ds_read_b128 v[228:231], v245 offset:2048
	ds_read_b128 v[232:235], v244 offset:4096
	ds_read_b128 v[236:239], v245 offset:4096
	s_waitcnt lgkmcnt(0)
	v_mfma_f32_32x32x16_bf16 v[0:15], v[216:219], v[224:227], v[0:15]
	v_mfma_f32_32x32x16_bf16 v[0:15], v[220:223], v[228:231], v[0:15]
	v_mfma_f32_32x32x16_bf16 v[16:31], v[216:219], v[232:235], v[16:31]
	v_mfma_f32_32x32x16_bf16 v[16:31], v[220:223], v[236:239], v[16:31]
	global_load_dwordx4 v[216:219], v[240:241], off offset:448
	global_load_dwordx4 v[220:223], v[242:243], off offset:448
	global_load_dwordx4 v[224:227], v[248:249], off offset:448
	global_load_dwordx4 v[228:231], v[250:251], off offset:448
	global_load_dwordx4 v[232:235], v[252:253], off offset:448
	global_load_dwordx4 v[236:239], v[254:255], off offset:448
	s_waitcnt vmcnt(18)
	ds_write_b128 v194, v[82:85]
	ds_write_b128 v194, v[86:89] offset:1024
	ds_write_b128 v194, v[90:93] offset:2048
	ds_write_b128 v194, v[94:97] offset:3072
	ds_write_b128 v194, v[98:101] offset:4096
	ds_write_b128 v194, v[102:105] offset:5120
	ds_read_b128 v[82:85], v244
	ds_read_b128 v[86:89], v245
	ds_read_b128 v[90:93], v244 offset:2048
	ds_read_b128 v[94:97], v245 offset:2048
	ds_read_b128 v[98:101], v244 offset:4096
	ds_read_b128 v[102:105], v245 offset:4096
	s_waitcnt lgkmcnt(0)
	v_mfma_f32_32x32x16_bf16 v[0:15], v[82:85], v[90:93], v[0:15]
	v_mfma_f32_32x32x16_bf16 v[0:15], v[86:89], v[94:97], v[0:15]
	v_mfma_f32_32x32x16_bf16 v[16:31], v[82:85], v[98:101], v[16:31]
	v_mfma_f32_32x32x16_bf16 v[16:31], v[86:89], v[102:105], v[16:31]
	global_load_dwordx4 v[82:85], v[240:241], off offset:512
	global_load_dwordx4 v[86:89], v[242:243], off offset:512
	global_load_dwordx4 v[90:93], v[248:249], off offset:512
	global_load_dwordx4 v[94:97], v[250:251], off offset:512
	global_load_dwordx4 v[98:101], v[252:253], off offset:512
	global_load_dwordx4 v[102:105], v[254:255], off offset:512
	s_waitcnt vmcnt(18)
	ds_write_b128 v194, v[106:109]
	ds_write_b128 v194, v[110:113] offset:1024
	ds_write_b128 v194, v[132:135] offset:2048
	ds_write_b128 v194, v[136:139] offset:3072
	ds_write_b128 v194, v[140:143] offset:4096
	ds_write_b128 v194, v[144:147] offset:5120
	ds_read_b128 v[106:109], v244
	ds_read_b128 v[110:113], v245
	ds_read_b128 v[132:135], v244 offset:2048
	ds_read_b128 v[136:139], v245 offset:2048
	ds_read_b128 v[140:143], v244 offset:4096
	ds_read_b128 v[144:147], v245 offset:4096
	s_waitcnt lgkmcnt(0)
	v_mfma_f32_32x32x16_bf16 v[0:15], v[106:109], v[132:135], v[0:15]
	v_mfma_f32_32x32x16_bf16 v[0:15], v[110:113], v[136:139], v[0:15]
	v_mfma_f32_32x32x16_bf16 v[16:31], v[106:109], v[140:143], v[16:31]
	v_mfma_f32_32x32x16_bf16 v[16:31], v[110:113], v[144:147], v[16:31]
	global_load_dwordx4 v[106:109], v[240:241], off offset:576
	global_load_dwordx4 v[110:113], v[242:243], off offset:576
	global_load_dwordx4 v[132:135], v[248:249], off offset:576
	global_load_dwordx4 v[136:139], v[250:251], off offset:576
	global_load_dwordx4 v[140:143], v[252:253], off offset:576
	global_load_dwordx4 v[144:147], v[254:255], off offset:576
	s_waitcnt vmcnt(18)
	ds_write_b128 v194, v[148:151]
	ds_write_b128 v194, v[166:169] offset:1024
	ds_write_b128 v194, v[170:173] offset:2048
	ds_write_b128 v194, v[174:177] offset:3072
	ds_write_b128 v194, v[198:201] offset:4096
	ds_write_b128 v194, v[202:205] offset:5120
	ds_read_b128 v[148:151], v244
	ds_read_b128 v[166:169], v245
	ds_read_b128 v[170:173], v244 offset:2048
	ds_read_b128 v[174:177], v245 offset:2048
	ds_read_b128 v[198:201], v244 offset:4096
	ds_read_b128 v[202:205], v245 offset:4096
	s_waitcnt lgkmcnt(0)
	v_mfma_f32_32x32x16_bf16 v[0:15], v[148:151], v[170:173], v[0:15]
	v_mfma_f32_32x32x16_bf16 v[0:15], v[166:169], v[174:177], v[0:15]
	v_mfma_f32_32x32x16_bf16 v[16:31], v[148:151], v[198:201], v[16:31]
	v_mfma_f32_32x32x16_bf16 v[16:31], v[166:169], v[202:205], v[16:31]
	global_load_dwordx4 v[148:151], v[240:241], off offset:640
	global_load_dwordx4 v[166:169], v[242:243], off offset:640
	global_load_dwordx4 v[170:173], v[248:249], off offset:640
	global_load_dwordx4 v[174:177], v[250:251], off offset:640
	global_load_dwordx4 v[198:201], v[252:253], off offset:640
	global_load_dwordx4 v[202:205], v[254:255], off offset:640
	s_waitcnt vmcnt(18)
; #define LAS __attribute__((address_space(3)))
; DI float bflo(unsigned u) { return __uint_as_float(u << 16); }
; DI float bfhi(unsigned u) { return __uint_as_float(u & 0xffff0000u); }
;     DI void operator()(const f32x4 v, int row, int pn, int wc, int bj, int cl) const {
;     ...
;         else { const u32x2 w = *(const u32x2*)(XN + (size_t)row * D + col); x = (f32x4){bflo(w.x), bfhi(w.x), bflo(w.y), bfhi(w.y)}; }
;         x += v;
;         if (MODE == 2) *(f32x4*)(out + (size_t)row * D + col) = x;
; template <class EpiS>
; DI void sample_gemm(LAS unsigned char* lds, const bf16_t* A, const bf16_t* Bt, int nN, int K, const EpiS& E) {
;     ...
;         __syncthreads();
;         LAS float* part = (LAS float*)(lds + w * 8192);
; #pragma unroll
;         for (int r = 0; r < 16; ++r) { const int row = (r & 3) + 8 * (r >> 2) + 4 * h; part[row * 64 + r32] = c0[r]; part[row * 64 + 32 + r32] = c1[r]; }
;         __syncthreads();
;         f32x4 v = (f32x4){0.f, 0.f, 0.f, 0.f};
; #pragma unroll
;         for (int ww = 0; ww < 8; ++ww) v += *(const LAS f32x4*)(lds + ww * 8192 + (tid >> 4) * 256 + (tid & 15) * 16);
;         E(v, MP + rb * 32 + (tid >> 4), pn, wc, (tid >> 3) & 1, 4 * (tid & 7));
	ds_write_b128 v194, v[216:219]
	ds_write_b128 v194, v[220:223] offset:1024
	ds_write_b128 v194, v[224:227] offset:2048
	ds_write_b128 v194, v[228:231] offset:3072
	ds_write_b128 v194, v[232:235] offset:4096
	ds_write_b128 v194, v[236:239] offset:5120
	ds_read_b128 v[216:219], v244
	ds_read_b128 v[220:223], v245
	ds_read_b128 v[224:227], v244 offset:2048
	ds_read_b128 v[228:231], v245 offset:2048
	ds_read_b128 v[232:235], v244 offset:4096
	ds_read_b128 v[236:239], v245 offset:4096
	s_waitcnt lgkmcnt(0)
	v_mfma_f32_32x32x16_bf16 v[0:15], v[216:219], v[224:227], v[0:15]
	v_mfma_f32_32x32x16_bf16 v[0:15], v[220:223], v[228:231], v[0:15]
	v_mfma_f32_32x32x16_bf16 v[16:31], v[216:219], v[232:235], v[16:31]
	v_mfma_f32_32x32x16_bf16 v[16:31], v[220:223], v[236:239], v[16:31]
	s_waitcnt vmcnt(12)
	ds_write_b128 v194, v[82:85]
	ds_write_b128 v194, v[86:89] offset:1024
	ds_write_b128 v194, v[90:93] offset:2048
	ds_write_b128 v194, v[94:97] offset:3072
	ds_write_b128 v194, v[98:101] offset:4096
	ds_write_b128 v194, v[102:105] offset:5120
	ds_read_b128 v[82:85], v244
	ds_read_b128 v[86:89], v245
	ds_read_b128 v[90:93], v244 offset:2048
	ds_read_b128 v[94:97], v245 offset:2048
	ds_read_b128 v[98:101], v244 offset:4096
	ds_read_b128 v[102:105], v245 offset:4096
	s_waitcnt lgkmcnt(0)
	v_mfma_f32_32x32x16_bf16 v[0:15], v[82:85], v[90:93], v[0:15]
	v_mfma_f32_32x32x16_bf16 v[0:15], v[86:89], v[94:97], v[0:15]
	v_mfma_f32_32x32x16_bf16 v[16:31], v[82:85], v[98:101], v[16:31]
	v_mfma_f32_32x32x16_bf16 v[16:31], v[86:89], v[102:105], v[16:31]
	s_waitcnt vmcnt(6)
	ds_write_b128 v194, v[106:109]
	ds_write_b128 v194, v[110:113] offset:1024
	ds_write_b128 v194, v[132:135] offset:2048
	ds_write_b128 v194, v[136:139] offset:3072
	ds_write_b128 v194, v[140:143] offset:4096
	ds_write_b128 v194, v[144:147] offset:5120
	ds_read_b128 v[106:109], v244
	ds_read_b128 v[110:113], v245
	ds_read_b128 v[132:135], v244 offset:2048
	ds_read_b128 v[136:139], v245 offset:2048
	ds_read_b128 v[140:143], v244 offset:4096
	ds_read_b128 v[144:147], v245 offset:4096
	s_waitcnt lgkmcnt(0)
	v_mfma_f32_32x32x16_bf16 v[0:15], v[106:109], v[132:135], v[0:15]
	v_mfma_f32_32x32x16_bf16 v[0:15], v[110:113], v[136:139], v[0:15]
	v_mfma_f32_32x32x16_bf16 v[16:31], v[106:109], v[140:143], v[16:31]
	v_mfma_f32_32x32x16_bf16 v[16:31], v[110:113], v[144:147], v[16:31]
	s_waitcnt vmcnt(0)
	ds_write_b128 v194, v[148:151]
	ds_write_b128 v194, v[166:169] offset:1024
	ds_write_b128 v194, v[170:173] offset:2048
	ds_write_b128 v194, v[174:177] offset:3072
	ds_write_b128 v194, v[198:201] offset:4096
	ds_write_b128 v194, v[202:205] offset:5120
	ds_read_b128 v[148:151], v244
	ds_read_b128 v[166:169], v245
	ds_read_b128 v[170:173], v244 offset:2048
	ds_read_b128 v[174:177], v245 offset:2048
	ds_read_b128 v[198:201], v244 offset:4096
	ds_read_b128 v[202:205], v245 offset:4096
	s_waitcnt lgkmcnt(0)
	v_mfma_f32_32x32x16_bf16 v[0:15], v[148:151], v[170:173], v[0:15]
	v_mfma_f32_32x32x16_bf16 v[0:15], v[166:169], v[174:177], v[0:15]
	v_mfma_f32_32x32x16_bf16 v[16:31], v[148:151], v[198:201], v[16:31]
	v_mfma_f32_32x32x16_bf16 v[16:31], v[166:169], v[202:205], v[16:31]
	s_barrier
	s_nop 11
	ds_write2_b32 v39, v0, v16 offset1:32
	ds_write2_b32 v39, v1, v17 offset0:64 offset1:96
	ds_write2_b32 v39, v2, v18 offset0:128 offset1:160
	ds_write2_b32 v39, v3, v19 offset0:192 offset1:224
	ds_write2_b32 v43, v4, v20 offset1:32
	ds_write2_b32 v43, v5, v21 offset0:64 offset1:96
	ds_write2_b32 v43, v6, v22 offset0:128 offset1:160
	ds_write2_b32 v43, v7, v23 offset0:192 offset1:224
	ds_write2_b32 v44, v8, v24 offset1:32
	ds_write2_b32 v44, v9, v25 offset0:64 offset1:96
	ds_write2_b32 v44, v10, v26 offset0:128 offset1:160
	ds_write2_b32 v44, v11, v27 offset0:192 offset1:224
	ds_write2_b32 v45, v12, v28 offset1:32
	ds_write2_b32 v45, v13, v29 offset0:64 offset1:96
	ds_write2_b32 v45, v14, v30 offset0:128 offset1:160
	ds_write2_b32 v45, v15, v31 offset0:192 offset1:224
	s_waitcnt lgkmcnt(0)
	s_barrier
	v_lshl_add_u64 v[0:1], s[74:75], 0, v[32:33]
	v_lshl_add_u64 v[48:49], v[58:59], 2, v[0:1]
	ds_read_b128 v[0:3], v42
	ds_read_b128 v[4:7], v42 offset:8192
	ds_read_b128 v[8:11], v42 offset:16384
	ds_read_b128 v[12:15], v42 offset:24576
	ds_read_b128 v[16:19], v42 offset:32768
	ds_read_b128 v[20:23], v42 offset:40960
	ds_read_b128 v[24:27], v42 offset:49152
	ds_read_b128 v[28:31], v42 offset:57344
	s_waitcnt lgkmcnt(7)
	v_pk_add_f32 v[2:3], v[2:3], 0 op_sel_hi:[1,0]
	v_pk_add_f32 v[0:1], v[0:1], 0 op_sel_hi:[1,0]
	s_waitcnt lgkmcnt(6)
	v_pk_add_f32 v[2:3], v[2:3], v[6:7]
	v_pk_add_f32 v[0:1], v[0:1], v[4:5]
	s_waitcnt lgkmcnt(5)
	v_pk_add_f32 v[2:3], v[2:3], v[10:11]
	v_pk_add_f32 v[0:1], v[0:1], v[8:9]
	s_waitcnt lgkmcnt(4)
	v_pk_add_f32 v[2:3], v[2:3], v[14:15]
	v_pk_add_f32 v[0:1], v[0:1], v[12:13]
	s_waitcnt lgkmcnt(3)
	v_pk_add_f32 v[2:3], v[2:3], v[18:19]
	v_pk_add_f32 v[0:1], v[0:1], v[16:17]
	s_waitcnt lgkmcnt(2)
	v_pk_add_f32 v[2:3], v[2:3], v[22:23]
	v_pk_add_f32 v[0:1], v[0:1], v[20:21]
	s_waitcnt lgkmcnt(1)
	v_pk_add_f32 v[2:3], v[2:3], v[26:27]
	v_pk_add_f32 v[0:1], v[0:1], v[24:25]
	s_waitcnt lgkmcnt(0)
	v_pk_add_f32 v[2:3], v[2:3], v[30:31]
	v_pk_add_f32 v[0:1], v[0:1], v[28:29]
	s_waitcnt vmcnt(0)
	v_lshlrev_b32_e32 v4, 16, v208
	v_and_b32_e32 v5, 0xffff0000, v208
	v_lshlrev_b32_e32 v6, 16, v209
	v_and_b32_e32 v7, 0xffff0000, v209
	v_pk_add_f32 v[0:1], v[0:1], v[4:5]
	v_pk_add_f32 v[2:3], v[2:3], v[6:7]
	global_store_dwordx4 v[48:49], v[0:3], off
	s_cbranch_scc1 .LBB0_1522
